# sample SSD: dt values by vector loads instead of scalar loads (scalar cache is not coherent with data written earlier in the launch)
# speedup vs baseline: 1.0186x; 1.0001x over previous
; __device__ __forceinline__ float bf2f(unsigned h) { return __uint_as_float(h << 16); }
; __device__ __forceinline__ void ssd_sample_items(LAS unsigned char* lds, int it0, int itstride, int nitems, const bf16_t* XBC, const float* DT, const float* a_log,
;                                                  const float* state_in, bf16_t* MIX, float* s_ssm) {
;     ...
;     { const int b = it0 >> 2, g = it0 & 3, h = g * 8 + w; const float* sp = state_in + (size_t)(b * NH + h) * HP * NS;
; #pragma unroll
;       for (int k = 0; k < 16; ++k) nx[k] = *(const f32x4*)(sp + k * 256 + lane * 4); }
;     for (int it = it0; it < nitems; it += itstride) {
;         const int b = it >> 2, g = it & 3, h = g * 8 + w;
;         u32x2 Bp[4], Cp[4]; float dtv[4];
; #pragma unroll
;         for (int t = 0; t < 4; ++t) { const size_t row = (size_t)(MP + 4 * b + t);
;             Xs[t * 512 + tid] = bf2f(XBC[row * XBCW + g * 512 + tid]);
;             Bp[t] = *(const u32x2*)(XBC + row * XBCW + 2048 + g * 128 + 4 * nl); Cp[t] = *(const u32x2*)(XBC + row * XBCW + 2560 + g * 128 + 4 * nl);
;             dtv[t] = DT[row * NH + h]; }
;         const float A = -__expf(a_log[h]);
.Lssds_begin:
	s_load_dwordx4 s[24:27], s[0:1], 0xc8
	s_load_dwordx2 s[14:15], s[0:1], 0x10
	s_load_dwordx2 s[16:17], s[0:1], 0x58
	s_mov_b32 s47, s4
	s_lshr_b32 s46, s6, 6
	v_readlane_b32 s21, v253, 20
	v_and_b32_e32 v213, 63, v212
	v_lshrrev_b32_e32 v133, 4, v213
	v_and_b32_e32 v134, 15, v213
	v_lshlrev_b32_e32 v132, 12, v133
	v_lshl_add_u32 v132, v134, 4, v132
	v_lshlrev_b32_e32 v133, 4, v133
	v_lshlrev_b32_e32 v134, 3, v134
	v_mov_b32_e32 v250, 0
	s_mov_b32 s38, 0x55555555
	s_mov_b32 s39, 0x55555555
	s_mov_b32 s68, 0xcccccccc
	s_mov_b32 s69, 0xcccccccc
	s_sub_u32 s33, s94, s21
	s_mov_b32 s48, 1
	s_waitcnt lgkmcnt(0)
	s_add_u32 s40, s26, 0x135d0000
	s_addc_u32 s41, s27, 0
	s_add_u32 s42, s26, 0x9780000
	s_addc_u32 s43, s27, 0
	s_add_u32 s44, s26, 0x1acd0000
	s_addc_u32 s45, s27, 0
	s_add_u32 s18, s24, 0x496a000
	s_addc_u32 s19, s25, 0
	s_lshr_b32 s20, s47, 2
	s_and_b32 s21, s47, 3
	s_lshl_b32 s22, s21, 3
	s_add_u32 s22, s22, s46
	s_lshl_b32 s23, s20, 5
	s_add_u32 s23, s23, s22
	s_lshr_b32 s51, s23, 17
	s_lshl_b32 s50, s23, 15
	s_add_u32 s52, s18, s50
	s_addc_u32 s53, s19, s51
	s_add_u32 s50, s14, s50
	s_addc_u32 s51, s15, s51
	s_add_u32 s54, s50, 0x4000
	s_addc_u32 s55, s51, 0
	s_add_u32 s56, s52, 0x4000
	s_addc_u32 s57, s53, 0
	s_lshl_b32 s20, s20, 2
	s_add_u32 s20, s20, 0x2000
	s_lshl_b32 s23, s22, 7
	s_mul_hi_u32 s59, s20, 0x1800
	s_mul_i32 s58, s20, 0x1800
	s_add_u32 s58, s58, s40
	s_addc_u32 s59, s59, s41
	s_add_u32 s58, s58, s23
	s_addc_u32 s59, s59, 0
	s_add_u32 s60, s58, 0x1800
	s_addc_u32 s61, s59, 0
	s_add_u32 s62, s60, 0x1800
	s_addc_u32 s63, s61, 0
	s_add_u32 s64, s62, 0x1800
	s_addc_u32 s65, s63, 0
	s_lshr_b32 s5, s20, 19
	s_lshl_b32 s4, s20, 13
	s_add_u32 s4, s4, s44
	s_addc_u32 s5, s5, s45
	s_add_u32 s4, s4, s23
	s_addc_u32 s5, s5, 0
	s_add_u32 s6, s4, 0x2000
	s_addc_u32 s7, s5, 0
	s_add_u32 s8, s6, 0x2000
	s_addc_u32 s9, s7, 0
	s_add_u32 s10, s8, 0x2000
	s_addc_u32 s11, s9, 0
	s_lshl_b32 s23, s22, 2
	s_lshr_b32 s21, s20, 25
	s_lshl_b32 s20, s20, 7
	s_add_u32 s20, s20, s42
	s_addc_u32 s21, s21, s43
	s_add_u32 s20, s20, s23
	s_addc_u32 s21, s21, 0
	global_load_dword v208, v250, s[20:21] offset:0
	global_load_dword v209, v250, s[20:21] offset:128
	global_load_dword v210, v250, s[20:21] offset:256
	global_load_dword v211, v250, s[20:21] offset:384
	s_nop 0
	s_add_u32 s20, s16, s23
	s_addc_u32 s21, s17, 0
	s_load_dword s36, s[20:21], 0x0
	global_load_dwordx4 v[0:3], v132, s[50:51] offset:0
	global_load_dwordx4 v[4:7], v132, s[50:51] offset:256
	global_load_dwordx4 v[8:11], v132, s[50:51] offset:512
	global_load_dwordx4 v[12:15], v132, s[50:51] offset:768
	global_load_dwordx4 v[16:19], v132, s[50:51] offset:1024
	global_load_dwordx4 v[20:23], v132, s[50:51] offset:1280
	global_load_dwordx4 v[24:27], v132, s[50:51] offset:1536
	global_load_dwordx4 v[28:31], v132, s[50:51] offset:1792
	global_load_dwordx4 v[32:35], v132, s[50:51] offset:2048
	global_load_dwordx4 v[36:39], v132, s[50:51] offset:2304
	global_load_dwordx4 v[40:43], v132, s[50:51] offset:2560
	global_load_dwordx4 v[44:47], v132, s[50:51] offset:2816
	global_load_dwordx4 v[48:51], v132, s[50:51] offset:3072
	global_load_dwordx4 v[52:55], v132, s[50:51] offset:3328
	global_load_dwordx4 v[56:59], v132, s[50:51] offset:3584
	global_load_dwordx4 v[60:63], v132, s[50:51] offset:3840
	s_and_b32 s20, s47, 3
	s_lshl_b32 s20, s20, 8
	s_lshl_b32 s21, s22, 7
	s_sub_u32 s20, s20, s21
	s_add_u32 s20, s20, 0x1000
	s_add_u32 s22, s58, s20
	s_addc_u32 s23, s59, 0
	global_load_dwordx2 v[136:137], v134, s[22:23]
	global_load_dwordx2 v[138:139], v134, s[22:23] offset:128
	global_load_dwordx2 v[152:153], v134, s[22:23] offset:1024
	global_load_dwordx2 v[154:155], v134, s[22:23] offset:1152
	s_add_u32 s22, s60, s20
	s_addc_u32 s23, s61, 0
	global_load_dwordx2 v[140:141], v134, s[22:23]
	global_load_dwordx2 v[142:143], v134, s[22:23] offset:128
	global_load_dwordx2 v[156:157], v134, s[22:23] offset:1024
	global_load_dwordx2 v[158:159], v134, s[22:23] offset:1152
	s_add_u32 s22, s62, s20
	s_addc_u32 s23, s63, 0
	global_load_dwordx2 v[144:145], v134, s[22:23]
	global_load_dwordx2 v[146:147], v134, s[22:23] offset:128
	global_load_dwordx2 v[160:161], v134, s[22:23] offset:1024
	global_load_dwordx2 v[162:163], v134, s[22:23] offset:1152
	s_add_u32 s22, s64, s20
	s_addc_u32 s23, s65, 0
	global_load_dwordx2 v[148:149], v134, s[22:23]
	global_load_dwordx2 v[150:151], v134, s[22:23] offset:128
	global_load_dwordx2 v[164:165], v134, s[22:23] offset:1024
	global_load_dwordx2 v[166:167], v134, s[22:23] offset:1152
	global_load_dwordx4 v[168:171], v133, s[58:59] offset:0
	global_load_dwordx4 v[184:187], v133, s[58:59] offset:64
	global_load_dwordx4 v[172:175], v133, s[60:61] offset:0
	global_load_dwordx4 v[188:191], v133, s[60:61] offset:64
	global_load_dwordx4 v[176:179], v133, s[62:63] offset:0
	global_load_dwordx4 v[192:195], v133, s[62:63] offset:64
	global_load_dwordx4 v[180:183], v133, s[64:65] offset:0
	global_load_dwordx4 v[196:199], v133, s[64:65] offset:64

; __device__ __forceinline__ float bf2f(unsigned h) { return __uint_as_float(h << 16); }
; __device__ __forceinline__ void ssd_sample_items(LAS unsigned char* lds, int it0, int itstride, int nitems, const bf16_t* XBC, const float* DT, const float* a_log,
;                                                  const float* state_in, bf16_t* MIX, float* s_ssm) {
;     ...
;         const float A = -__expf(a_log[h]);
;     ...
;                 const float dt = dtv[t]; const float da = __expf(dt * A);
;                 const f32x4 Bt = (f32x4){bf2f(Bp[t].x & 0xffffu), bf2f(Bp[t].x >> 16), bf2f(Bp[t].y & 0xffffu), bf2f(Bp[t].y >> 16)} * dt;
;                 const f32x4 Ct = (f32x4){bf2f(Cp[t].x & 0xffffu), bf2f(Cp[t].x >> 16), bf2f(Cp[t].y & 0xffffu), bf2f(Cp[t].y >> 16)};
;                 float part[8];
;                 { const bool up8 = (nl & 8) != 0;
; #pragma unroll
;                   for (int i = 0; i < 8; ++i) {
;                     const float x0 = Xs[t * 512 + w * 64 + 32 * hh + 2 * i + half], x1 = Xs[t * 512 + w * 64 + 32 * hh + 2 * (i + 8) + half];
;                     st[i] = st[i] * da + Bt * x0; st[i + 8] = st[i + 8] * da + Bt * x1;
;                     const f32x4 q0 = Ct * st[i], q1 = Ct * st[i + 8];
;                     const float p0 = (q0.x + q0.y) + (q0.z + q0.w), p1 = (q1.x + q1.y) + (q1.z + q1.w);
;                     const float send = up8 ? p0 : p1, keep = up8 ? p1 : p0; part[i] = keep + __shfl_xor(send, 8); } }
.Lssds_wd:
	s_mov_b32 s48, 0
	s_waitcnt lgkmcnt(0)
	v_mov_b32_e32 v248, s36
	v_mul_f32_e32 v248, 0x3fb8aa3b, v248
	v_exp_f32_e32 v248, v248
	s_nop 0
	v_mul_f32_e32 v128, v208, v248
	v_mul_f32_e32 v128, 0xbfb8aa3b, v128
	v_exp_f32_e32 v128, v128
	v_mul_f32_e32 v129, v209, v248
	v_mul_f32_e32 v129, 0xbfb8aa3b, v129
	v_exp_f32_e32 v129, v129
	v_mul_f32_e32 v130, v210, v248
	v_mul_f32_e32 v130, 0xbfb8aa3b, v130
	v_exp_f32_e32 v130, v130
	v_mul_f32_e32 v131, v211, v248
	v_mul_f32_e32 v131, 0xbfb8aa3b, v131
	v_exp_f32_e32 v131, v131
	s_nop 0
	v_lshlrev_b32_e32 v224, 16, v168
	v_and_b32_e32 v225, 0xffff0000, v168
	v_lshlrev_b32_e32 v226, 16, v169
	v_and_b32_e32 v227, 0xffff0000, v169
	v_lshlrev_b32_e32 v228, 16, v170
	v_and_b32_e32 v229, 0xffff0000, v170
	v_lshlrev_b32_e32 v230, 16, v171
	v_and_b32_e32 v231, 0xffff0000, v171
	v_lshlrev_b32_e32 v200, 16, v136
	v_and_b32_e32 v201, 0xffff0000, v136
	v_lshlrev_b32_e32 v202, 16, v137
	v_and_b32_e32 v203, 0xffff0000, v137
	v_lshlrev_b32_e32 v204, 16, v138
	v_and_b32_e32 v205, 0xffff0000, v138
	v_lshlrev_b32_e32 v206, 16, v139
	v_and_b32_e32 v207, 0xffff0000, v139
	v_lshlrev_b32_e32 v216, 16, v152
	v_and_b32_e32 v217, 0xffff0000, v152
	v_lshlrev_b32_e32 v218, 16, v153
	v_and_b32_e32 v219, 0xffff0000, v153
	v_lshlrev_b32_e32 v220, 16, v154
	v_and_b32_e32 v221, 0xffff0000, v154
	v_lshlrev_b32_e32 v222, 16, v155
	v_and_b32_e32 v223, 0xffff0000, v155
	v_pk_mul_f32 v[200:201], v[200:201], v[208:209] op_sel:[0,0] op_sel_hi:[1,0]
	v_pk_mul_f32 v[202:203], v[202:203], v[208:209] op_sel:[0,0] op_sel_hi:[1,0]
	v_pk_mul_f32 v[204:205], v[204:205], v[208:209] op_sel:[0,0] op_sel_hi:[1,0]
	v_pk_mul_f32 v[206:207], v[206:207], v[208:209] op_sel:[0,0] op_sel_hi:[1,0]
	v_pk_mul_f32 v[0:1], v[0:1], v[128:129] op_sel:[0,0] op_sel_hi:[1,0]
	v_pk_mul_f32 v[2:3], v[2:3], v[128:129] op_sel:[0,0] op_sel_hi:[1,0]
	v_pk_fma_f32 v[0:1], v[200:201], v[224:225], v[0:1] op_sel:[0,0,0] op_sel_hi:[1,0,1]
	v_pk_fma_f32 v[2:3], v[202:203], v[224:225], v[2:3] op_sel:[0,0,0] op_sel_hi:[1,0,1]
	v_pk_mul_f32 v[4:5], v[4:5], v[128:129] op_sel:[0,0] op_sel_hi:[1,0]
	v_pk_mul_f32 v[6:7], v[6:7], v[128:129] op_sel:[0,0] op_sel_hi:[1,0]
	v_pk_fma_f32 v[4:5], v[204:205], v[224:225], v[4:5] op_sel:[0,0,0] op_sel_hi:[1,0,1]
	v_pk_fma_f32 v[6:7], v[206:207], v[224:225], v[6:7] op_sel:[0,0,0] op_sel_hi:[1,0,1]
	v_pk_mul_f32 v[240:241], v[216:217], v[0:1]
	v_pk_fma_f32 v[240:241], v[218:219], v[2:3], v[240:241]
	v_pk_fma_f32 v[240:241], v[220:221], v[4:5], v[240:241]
	v_pk_fma_f32 v[240:241], v[222:223], v[6:7], v[240:241]
	v_add_f32_e32 v232, v240, v241
	v_pk_mul_f32 v[8:9], v[8:9], v[128:129] op_sel:[0,0] op_sel_hi:[1,0]
	v_pk_mul_f32 v[10:11], v[10:11], v[128:129] op_sel:[0,0] op_sel_hi:[1,0]
	v_pk_fma_f32 v[8:9], v[200:201], v[224:225], v[8:9] op_sel:[0,1,0] op_sel_hi:[1,1,1]
	v_pk_fma_f32 v[10:11], v[202:203], v[224:225], v[10:11] op_sel:[0,1,0] op_sel_hi:[1,1,1]
	v_pk_mul_f32 v[12:13], v[12:13], v[128:129] op_sel:[0,0] op_sel_hi:[1,0]
	v_pk_mul_f32 v[14:15], v[14:15], v[128:129] op_sel:[0,0] op_sel_hi:[1,0]
	v_pk_fma_f32 v[12:13], v[204:205], v[224:225], v[12:13] op_sel:[0,1,0] op_sel_hi:[1,1,1]
	v_pk_fma_f32 v[14:15], v[206:207], v[224:225], v[14:15] op_sel:[0,1,0] op_sel_hi:[1,1,1]
	v_pk_mul_f32 v[242:243], v[216:217], v[8:9]
	v_pk_fma_f32 v[242:243], v[218:219], v[10:11], v[242:243]
	v_pk_fma_f32 v[242:243], v[220:221], v[12:13], v[242:243]
	v_pk_fma_f32 v[242:243], v[222:223], v[14:15], v[242:243]
	v_add_f32_e32 v233, v242, v243
	v_pk_mul_f32 v[16:17], v[16:17], v[128:129] op_sel:[0,0] op_sel_hi:[1,0]
	v_pk_mul_f32 v[18:19], v[18:19], v[128:129] op_sel:[0,0] op_sel_hi:[1,0]
	v_pk_fma_f32 v[16:17], v[200:201], v[226:227], v[16:17] op_sel:[0,0,0] op_sel_hi:[1,0,1]
	v_pk_fma_f32 v[18:19], v[202:203], v[226:227], v[18:19] op_sel:[0,0,0] op_sel_hi:[1,0,1]
	v_pk_mul_f32 v[20:21], v[20:21], v[128:129] op_sel:[0,0] op_sel_hi:[1,0]
	v_pk_mul_f32 v[22:23], v[22:23], v[128:129] op_sel:[0,0] op_sel_hi:[1,0]
	v_pk_fma_f32 v[20:21], v[204:205], v[226:227], v[20:21] op_sel:[0,0,0] op_sel_hi:[1,0,1]
	v_pk_fma_f32 v[22:23], v[206:207], v[226:227], v[22:23] op_sel:[0,0,0] op_sel_hi:[1,0,1]
	v_pk_mul_f32 v[244:245], v[216:217], v[16:17]
	v_pk_fma_f32 v[244:245], v[218:219], v[18:19], v[244:245]
	v_pk_fma_f32 v[244:245], v[220:221], v[20:21], v[244:245]
	v_pk_fma_f32 v[244:245], v[222:223], v[22:23], v[244:245]
	v_add_f32_e32 v234, v244, v245
	v_pk_mul_f32 v[24:25], v[24:25], v[128:129] op_sel:[0,0] op_sel_hi:[1,0]
	v_pk_mul_f32 v[26:27], v[26:27], v[128:129] op_sel:[0,0] op_sel_hi:[1,0]
	v_pk_fma_f32 v[24:25], v[200:201], v[226:227], v[24:25] op_sel:[0,1,0] op_sel_hi:[1,1,1]
	v_pk_fma_f32 v[26:27], v[202:203], v[226:227], v[26:27] op_sel:[0,1,0] op_sel_hi:[1,1,1]
	v_pk_mul_f32 v[28:29], v[28:29], v[128:129] op_sel:[0,0] op_sel_hi:[1,0]
	v_pk_mul_f32 v[30:31], v[30:31], v[128:129] op_sel:[0,0] op_sel_hi:[1,0]
	v_pk_fma_f32 v[28:29], v[204:205], v[226:227], v[28:29] op_sel:[0,1,0] op_sel_hi:[1,1,1]
	v_pk_fma_f32 v[30:31], v[206:207], v[226:227], v[30:31] op_sel:[0,1,0] op_sel_hi:[1,1,1]
	v_pk_mul_f32 v[246:247], v[216:217], v[24:25]
	v_pk_fma_f32 v[246:247], v[218:219], v[26:27], v[246:247]
	v_pk_fma_f32 v[246:247], v[220:221], v[28:29], v[246:247]
	v_pk_fma_f32 v[246:247], v[222:223], v[30:31], v[246:247]
	v_add_f32_e32 v235, v246, v247
	v_pk_mul_f32 v[32:33], v[32:33], v[128:129] op_sel:[0,0] op_sel_hi:[1,0]
	v_pk_mul_f32 v[34:35], v[34:35], v[128:129] op_sel:[0,0] op_sel_hi:[1,0]
	v_pk_fma_f32 v[32:33], v[200:201], v[228:229], v[32:33] op_sel:[0,0,0] op_sel_hi:[1,0,1]
	v_pk_fma_f32 v[34:35], v[202:203], v[228:229], v[34:35] op_sel:[0,0,0] op_sel_hi:[1,0,1]
; __device__ __forceinline__ float bf2f(unsigned h) { return __uint_as_float(h << 16); }
; __device__ __forceinline__ unsigned f2bf(float f) { unsigned u = __float_as_uint(f); return (u + 0x7fffu + ((u >> 16) & 1u)) >> 16; }
; #define BFLY(o) do { const bool up = (nl & (o)) != 0; _Pragma("unroll") for (int i = 0; i < (o); ++i) { \
;                     const float send = up ? part[i] : part[i + (o)]; const float keep = up ? part[i + (o)] : part[i]; part[i] = keep + __shfl_xor(send, (o)); } } while (0)
; __device__ __forceinline__ void ssd_sample_items(LAS unsigned char* lds, int it0, int itstride, int nitems, const bf16_t* XBC, const float* DT, const float* a_log,
;                                                  const float* state_in, bf16_t* MIX, float* s_ssm) {
;     ...
;             for (int t = 0; t < 4; ++t) {
;                 const float dt = dtv[t]; const float da = __expf(dt * A);
;                 const f32x4 Bt = (f32x4){bf2f(Bp[t].x & 0xffffu), bf2f(Bp[t].x >> 16), bf2f(Bp[t].y & 0xffffu), bf2f(Bp[t].y >> 16)} * dt;
;                 const f32x4 Ct = (f32x4){bf2f(Cp[t].x & 0xffffu), bf2f(Cp[t].x >> 16), bf2f(Cp[t].y & 0xffffu), bf2f(Cp[t].y >> 16)};
;                 float part[8];
;                 { const bool up8 = (nl & 8) != 0;
; #pragma unroll
;                   for (int i = 0; i < 8; ++i) {
;                     const float x0 = Xs[t * 512 + w * 64 + 32 * hh + 2 * i + half], x1 = Xs[t * 512 + w * 64 + 32 * hh + 2 * (i + 8) + half];
;                     st[i] = st[i] * da + Bt * x0; st[i + 8] = st[i + 8] * da + Bt * x1;
;                     const f32x4 q0 = Ct * st[i], q1 = Ct * st[i + 8];
;                     const float p0 = (q0.x + q0.y) + (q0.z + q0.w), p1 = (q1.x + q1.y) + (q1.z + q1.w);
;                     const float send = up8 ? p0 : p1, keep = up8 ? p1 : p0; part[i] = keep + __shfl_xor(send, 8); } }
;     ...
;                 BFLY(4); BFLY(2); BFLY(1);
;     ...
;                 yv[t] = part[0] + __shfl_xor(part[0], 16);
;             }
;             const int pout = 32 * hh + 2 * (nl & 15) + half;
;             if ((nl & 16) == 0) {
; #pragma unroll
;                 for (int t = 0; t < 4; ++t) MIX[(size_t)(MP + 4 * b + t) * DMIX + h * 64 + pout] = (bf16_t)f2bf(yv[t]);
;             }
	v_pk_mul_f32 v[36:37], v[36:37], v[128:129] op_sel:[0,0] op_sel_hi:[1,0]
	v_pk_mul_f32 v[38:39], v[38:39], v[128:129] op_sel:[0,0] op_sel_hi:[1,0]
	v_pk_fma_f32 v[36:37], v[204:205], v[228:229], v[36:37] op_sel:[0,0,0] op_sel_hi:[1,0,1]
	v_pk_fma_f32 v[38:39], v[206:207], v[228:229], v[38:39] op_sel:[0,0,0] op_sel_hi:[1,0,1]
	v_pk_mul_f32 v[240:241], v[216:217], v[32:33]
	v_pk_fma_f32 v[240:241], v[218:219], v[34:35], v[240:241]
	v_pk_fma_f32 v[240:241], v[220:221], v[36:37], v[240:241]
	v_pk_fma_f32 v[240:241], v[222:223], v[38:39], v[240:241]
	v_add_f32_e32 v236, v240, v241
	v_pk_mul_f32 v[40:41], v[40:41], v[128:129] op_sel:[0,0] op_sel_hi:[1,0]
	v_pk_mul_f32 v[42:43], v[42:43], v[128:129] op_sel:[0,0] op_sel_hi:[1,0]
	v_pk_fma_f32 v[40:41], v[200:201], v[228:229], v[40:41] op_sel:[0,1,0] op_sel_hi:[1,1,1]
	v_pk_fma_f32 v[42:43], v[202:203], v[228:229], v[42:43] op_sel:[0,1,0] op_sel_hi:[1,1,1]
	v_pk_mul_f32 v[44:45], v[44:45], v[128:129] op_sel:[0,0] op_sel_hi:[1,0]
	v_pk_mul_f32 v[46:47], v[46:47], v[128:129] op_sel:[0,0] op_sel_hi:[1,0]
	v_pk_fma_f32 v[44:45], v[204:205], v[228:229], v[44:45] op_sel:[0,1,0] op_sel_hi:[1,1,1]
	v_pk_fma_f32 v[46:47], v[206:207], v[228:229], v[46:47] op_sel:[0,1,0] op_sel_hi:[1,1,1]
	v_pk_mul_f32 v[242:243], v[216:217], v[40:41]
	v_pk_fma_f32 v[242:243], v[218:219], v[42:43], v[242:243]
	v_pk_fma_f32 v[242:243], v[220:221], v[44:45], v[242:243]
	v_pk_fma_f32 v[242:243], v[222:223], v[46:47], v[242:243]
	v_add_f32_e32 v237, v242, v243
	v_pk_mul_f32 v[48:49], v[48:49], v[128:129] op_sel:[0,0] op_sel_hi:[1,0]
	v_pk_mul_f32 v[50:51], v[50:51], v[128:129] op_sel:[0,0] op_sel_hi:[1,0]
	v_pk_fma_f32 v[48:49], v[200:201], v[230:231], v[48:49] op_sel:[0,0,0] op_sel_hi:[1,0,1]
	v_pk_fma_f32 v[50:51], v[202:203], v[230:231], v[50:51] op_sel:[0,0,0] op_sel_hi:[1,0,1]
	v_pk_mul_f32 v[52:53], v[52:53], v[128:129] op_sel:[0,0] op_sel_hi:[1,0]
	v_pk_mul_f32 v[54:55], v[54:55], v[128:129] op_sel:[0,0] op_sel_hi:[1,0]
	v_pk_fma_f32 v[52:53], v[204:205], v[230:231], v[52:53] op_sel:[0,0,0] op_sel_hi:[1,0,1]
	v_pk_fma_f32 v[54:55], v[206:207], v[230:231], v[54:55] op_sel:[0,0,0] op_sel_hi:[1,0,1]
	v_pk_mul_f32 v[244:245], v[216:217], v[48:49]
	v_pk_fma_f32 v[244:245], v[218:219], v[50:51], v[244:245]
	v_pk_fma_f32 v[244:245], v[220:221], v[52:53], v[244:245]
	v_pk_fma_f32 v[244:245], v[222:223], v[54:55], v[244:245]
	v_add_f32_e32 v238, v244, v245
	v_pk_mul_f32 v[56:57], v[56:57], v[128:129] op_sel:[0,0] op_sel_hi:[1,0]
	v_pk_mul_f32 v[58:59], v[58:59], v[128:129] op_sel:[0,0] op_sel_hi:[1,0]
	v_pk_fma_f32 v[56:57], v[200:201], v[230:231], v[56:57] op_sel:[0,1,0] op_sel_hi:[1,1,1]
	v_pk_fma_f32 v[58:59], v[202:203], v[230:231], v[58:59] op_sel:[0,1,0] op_sel_hi:[1,1,1]
	v_pk_mul_f32 v[60:61], v[60:61], v[128:129] op_sel:[0,0] op_sel_hi:[1,0]
	v_pk_mul_f32 v[62:63], v[62:63], v[128:129] op_sel:[0,0] op_sel_hi:[1,0]
	v_pk_fma_f32 v[60:61], v[204:205], v[230:231], v[60:61] op_sel:[0,1,0] op_sel_hi:[1,1,1]
	v_pk_fma_f32 v[62:63], v[206:207], v[230:231], v[62:63] op_sel:[0,1,0] op_sel_hi:[1,1,1]
	v_pk_mul_f32 v[246:247], v[216:217], v[56:57]
	v_pk_fma_f32 v[246:247], v[218:219], v[58:59], v[246:247]
	v_pk_fma_f32 v[246:247], v[220:221], v[60:61], v[246:247]
	v_pk_fma_f32 v[246:247], v[222:223], v[62:63], v[246:247]
	v_add_f32_e32 v239, v246, v247
	v_add_f32_dpp v232, v232, v232 row_mirror row_mask:0xf bank_mask:0x3
	v_add_f32_dpp v232, v236, v236 row_mirror row_mask:0xf bank_mask:0xc
	v_add_f32_dpp v233, v233, v233 row_mirror row_mask:0xf bank_mask:0x3
	v_add_f32_dpp v233, v237, v237 row_mirror row_mask:0xf bank_mask:0xc
	v_add_f32_dpp v234, v234, v234 row_mirror row_mask:0xf bank_mask:0x3
	v_add_f32_dpp v234, v238, v238 row_mirror row_mask:0xf bank_mask:0xc
	v_add_f32_dpp v235, v235, v235 row_mirror row_mask:0xf bank_mask:0x3
	v_add_f32_dpp v235, v239, v239 row_mirror row_mask:0xf bank_mask:0xc
	v_add_f32_dpp v232, v232, v232 row_half_mirror row_mask:0xf bank_mask:0x5
	v_add_f32_dpp v232, v234, v234 row_half_mirror row_mask:0xf bank_mask:0xa
	v_add_f32_dpp v233, v233, v233 row_half_mirror row_mask:0xf bank_mask:0x5
	v_add_f32_dpp v233, v235, v235 row_half_mirror row_mask:0xf bank_mask:0xa
	v_add_f32_dpp v248, v232, v232 quad_perm:[2,3,0,1] row_mask:0xf bank_mask:0xf
	s_nop 0
	v_add_f32_dpp v249, v233, v233 quad_perm:[2,3,0,1] row_mask:0xf bank_mask:0xf
	v_cndmask_b32_e64 v232, v248, v249, s[68:69]
	s_nop 1
	v_add_f32_dpp v233, v232, v232 quad_perm:[1,0,3,2] row_mask:0xf bank_mask:0xf
	v_cvt_pk_bf16_f32 v214, v233, v233
	s_mov_b64 exec, s[38:39]
	global_store_short v213, v214, s[4:5] offset:0
	s_mov_b64 exec, -1
	v_lshlrev_b32_e32 v224, 16, v172
	v_and_b32_e32 v225, 0xffff0000, v172
	v_lshlrev_b32_e32 v226, 16, v173
	v_and_b32_e32 v227, 0xffff0000, v173
	v_lshlrev_b32_e32 v228, 16, v174
	v_and_b32_e32 v229, 0xffff0000, v174
	v_lshlrev_b32_e32 v230, 16, v175
	v_and_b32_e32 v231, 0xffff0000, v175
	v_lshlrev_b32_e32 v200, 16, v140
	v_and_b32_e32 v201, 0xffff0000, v140
	v_lshlrev_b32_e32 v202, 16, v141
	v_and_b32_e32 v203, 0xffff0000, v141
	v_lshlrev_b32_e32 v204, 16, v142
	v_and_b32_e32 v205, 0xffff0000, v142
	v_lshlrev_b32_e32 v206, 16, v143
	v_and_b32_e32 v207, 0xffff0000, v143
	v_lshlrev_b32_e32 v216, 16, v156
	v_and_b32_e32 v217, 0xffff0000, v156
	v_lshlrev_b32_e32 v218, 16, v157
	v_and_b32_e32 v219, 0xffff0000, v157
	v_lshlrev_b32_e32 v220, 16, v158
	v_and_b32_e32 v221, 0xffff0000, v158
	v_lshlrev_b32_e32 v222, 16, v159
	v_and_b32_e32 v223, 0xffff0000, v159
	v_pk_mul_f32 v[200:201], v[200:201], v[208:209] op_sel:[0,1] op_sel_hi:[1,1]
	v_pk_mul_f32 v[202:203], v[202:203], v[208:209] op_sel:[0,1] op_sel_hi:[1,1]
; __device__ __forceinline__ float bf2f(unsigned h) { return __uint_as_float(h << 16); }
; __device__ __forceinline__ void ssd_sample_items(LAS unsigned char* lds, int it0, int itstride, int nitems, const bf16_t* XBC, const float* DT, const float* a_log,
;                                                  const float* state_in, bf16_t* MIX, float* s_ssm) {
;     ...
;             for (int t = 0; t < 4; ++t) {
;                 const float dt = dtv[t]; const float da = __expf(dt * A);
;                 const f32x4 Bt = (f32x4){bf2f(Bp[t].x & 0xffffu), bf2f(Bp[t].x >> 16), bf2f(Bp[t].y & 0xffffu), bf2f(Bp[t].y >> 16)} * dt;
;                 const f32x4 Ct = (f32x4){bf2f(Cp[t].x & 0xffffu), bf2f(Cp[t].x >> 16), bf2f(Cp[t].y & 0xffffu), bf2f(Cp[t].y >> 16)};
;                 float part[8];
;                 { const bool up8 = (nl & 8) != 0;
; #pragma unroll
;                   for (int i = 0; i < 8; ++i) {
;                     const float x0 = Xs[t * 512 + w * 64 + 32 * hh + 2 * i + half], x1 = Xs[t * 512 + w * 64 + 32 * hh + 2 * (i + 8) + half];
;                     st[i] = st[i] * da + Bt * x0; st[i + 8] = st[i + 8] * da + Bt * x1;
;                     const f32x4 q0 = Ct * st[i], q1 = Ct * st[i + 8];
;                     const float p0 = (q0.x + q0.y) + (q0.z + q0.w), p1 = (q1.x + q1.y) + (q1.z + q1.w);
;                     const float send = up8 ? p0 : p1, keep = up8 ? p1 : p0; part[i] = keep + __shfl_xor(send, 8); } }
	v_pk_mul_f32 v[204:205], v[204:205], v[208:209] op_sel:[0,1] op_sel_hi:[1,1]
	v_pk_mul_f32 v[206:207], v[206:207], v[208:209] op_sel:[0,1] op_sel_hi:[1,1]
	v_pk_mul_f32 v[0:1], v[0:1], v[128:129] op_sel:[0,1] op_sel_hi:[1,1]
	v_pk_mul_f32 v[2:3], v[2:3], v[128:129] op_sel:[0,1] op_sel_hi:[1,1]
	v_pk_fma_f32 v[0:1], v[200:201], v[224:225], v[0:1] op_sel:[0,0,0] op_sel_hi:[1,0,1]
	v_pk_fma_f32 v[2:3], v[202:203], v[224:225], v[2:3] op_sel:[0,0,0] op_sel_hi:[1,0,1]
	v_pk_mul_f32 v[4:5], v[4:5], v[128:129] op_sel:[0,1] op_sel_hi:[1,1]
	v_pk_mul_f32 v[6:7], v[6:7], v[128:129] op_sel:[0,1] op_sel_hi:[1,1]
	v_pk_fma_f32 v[4:5], v[204:205], v[224:225], v[4:5] op_sel:[0,0,0] op_sel_hi:[1,0,1]
	v_pk_fma_f32 v[6:7], v[206:207], v[224:225], v[6:7] op_sel:[0,0,0] op_sel_hi:[1,0,1]
	v_pk_mul_f32 v[240:241], v[216:217], v[0:1]
	v_pk_fma_f32 v[240:241], v[218:219], v[2:3], v[240:241]
	v_pk_fma_f32 v[240:241], v[220:221], v[4:5], v[240:241]
	v_pk_fma_f32 v[240:241], v[222:223], v[6:7], v[240:241]
	v_add_f32_e32 v232, v240, v241
	v_pk_mul_f32 v[8:9], v[8:9], v[128:129] op_sel:[0,1] op_sel_hi:[1,1]
	v_pk_mul_f32 v[10:11], v[10:11], v[128:129] op_sel:[0,1] op_sel_hi:[1,1]
	v_pk_fma_f32 v[8:9], v[200:201], v[224:225], v[8:9] op_sel:[0,1,0] op_sel_hi:[1,1,1]
	v_pk_fma_f32 v[10:11], v[202:203], v[224:225], v[10:11] op_sel:[0,1,0] op_sel_hi:[1,1,1]
	v_pk_mul_f32 v[12:13], v[12:13], v[128:129] op_sel:[0,1] op_sel_hi:[1,1]
	v_pk_mul_f32 v[14:15], v[14:15], v[128:129] op_sel:[0,1] op_sel_hi:[1,1]
	v_pk_fma_f32 v[12:13], v[204:205], v[224:225], v[12:13] op_sel:[0,1,0] op_sel_hi:[1,1,1]
	v_pk_fma_f32 v[14:15], v[206:207], v[224:225], v[14:15] op_sel:[0,1,0] op_sel_hi:[1,1,1]
	v_pk_mul_f32 v[242:243], v[216:217], v[8:9]
	v_pk_fma_f32 v[242:243], v[218:219], v[10:11], v[242:243]
	v_pk_fma_f32 v[242:243], v[220:221], v[12:13], v[242:243]
	v_pk_fma_f32 v[242:243], v[222:223], v[14:15], v[242:243]
	v_add_f32_e32 v233, v242, v243
	v_pk_mul_f32 v[16:17], v[16:17], v[128:129] op_sel:[0,1] op_sel_hi:[1,1]
	v_pk_mul_f32 v[18:19], v[18:19], v[128:129] op_sel:[0,1] op_sel_hi:[1,1]
	v_pk_fma_f32 v[16:17], v[200:201], v[226:227], v[16:17] op_sel:[0,0,0] op_sel_hi:[1,0,1]
	v_pk_fma_f32 v[18:19], v[202:203], v[226:227], v[18:19] op_sel:[0,0,0] op_sel_hi:[1,0,1]
	v_pk_mul_f32 v[20:21], v[20:21], v[128:129] op_sel:[0,1] op_sel_hi:[1,1]
	v_pk_mul_f32 v[22:23], v[22:23], v[128:129] op_sel:[0,1] op_sel_hi:[1,1]
	v_pk_fma_f32 v[20:21], v[204:205], v[226:227], v[20:21] op_sel:[0,0,0] op_sel_hi:[1,0,1]
	v_pk_fma_f32 v[22:23], v[206:207], v[226:227], v[22:23] op_sel:[0,0,0] op_sel_hi:[1,0,1]
	v_pk_mul_f32 v[244:245], v[216:217], v[16:17]
	v_pk_fma_f32 v[244:245], v[218:219], v[18:19], v[244:245]
	v_pk_fma_f32 v[244:245], v[220:221], v[20:21], v[244:245]
	v_pk_fma_f32 v[244:245], v[222:223], v[22:23], v[244:245]
	v_add_f32_e32 v234, v244, v245
	v_pk_mul_f32 v[24:25], v[24:25], v[128:129] op_sel:[0,1] op_sel_hi:[1,1]
	v_pk_mul_f32 v[26:27], v[26:27], v[128:129] op_sel:[0,1] op_sel_hi:[1,1]
	v_pk_fma_f32 v[24:25], v[200:201], v[226:227], v[24:25] op_sel:[0,1,0] op_sel_hi:[1,1,1]
	v_pk_fma_f32 v[26:27], v[202:203], v[226:227], v[26:27] op_sel:[0,1,0] op_sel_hi:[1,1,1]
	v_pk_mul_f32 v[28:29], v[28:29], v[128:129] op_sel:[0,1] op_sel_hi:[1,1]
	v_pk_mul_f32 v[30:31], v[30:31], v[128:129] op_sel:[0,1] op_sel_hi:[1,1]
	v_pk_fma_f32 v[28:29], v[204:205], v[226:227], v[28:29] op_sel:[0,1,0] op_sel_hi:[1,1,1]
	v_pk_fma_f32 v[30:31], v[206:207], v[226:227], v[30:31] op_sel:[0,1,0] op_sel_hi:[1,1,1]
	v_pk_mul_f32 v[246:247], v[216:217], v[24:25]
	v_pk_fma_f32 v[246:247], v[218:219], v[26:27], v[246:247]
	v_pk_fma_f32 v[246:247], v[220:221], v[28:29], v[246:247]
	v_pk_fma_f32 v[246:247], v[222:223], v[30:31], v[246:247]
	v_add_f32_e32 v235, v246, v247
	v_pk_mul_f32 v[32:33], v[32:33], v[128:129] op_sel:[0,1] op_sel_hi:[1,1]
	v_pk_mul_f32 v[34:35], v[34:35], v[128:129] op_sel:[0,1] op_sel_hi:[1,1]
	v_pk_fma_f32 v[32:33], v[200:201], v[228:229], v[32:33] op_sel:[0,0,0] op_sel_hi:[1,0,1]
	v_pk_fma_f32 v[34:35], v[202:203], v[228:229], v[34:35] op_sel:[0,0,0] op_sel_hi:[1,0,1]
	v_pk_mul_f32 v[36:37], v[36:37], v[128:129] op_sel:[0,1] op_sel_hi:[1,1]
	v_pk_mul_f32 v[38:39], v[38:39], v[128:129] op_sel:[0,1] op_sel_hi:[1,1]
	v_pk_fma_f32 v[36:37], v[204:205], v[228:229], v[36:37] op_sel:[0,0,0] op_sel_hi:[1,0,1]
	v_pk_fma_f32 v[38:39], v[206:207], v[228:229], v[38:39] op_sel:[0,0,0] op_sel_hi:[1,0,1]
	v_pk_mul_f32 v[240:241], v[216:217], v[32:33]
	v_pk_fma_f32 v[240:241], v[218:219], v[34:35], v[240:241]
	v_pk_fma_f32 v[240:241], v[220:221], v[36:37], v[240:241]
	v_pk_fma_f32 v[240:241], v[222:223], v[38:39], v[240:241]
	v_add_f32_e32 v236, v240, v241
	v_pk_mul_f32 v[40:41], v[40:41], v[128:129] op_sel:[0,1] op_sel_hi:[1,1]
	v_pk_mul_f32 v[42:43], v[42:43], v[128:129] op_sel:[0,1] op_sel_hi:[1,1]
	v_pk_fma_f32 v[40:41], v[200:201], v[228:229], v[40:41] op_sel:[0,1,0] op_sel_hi:[1,1,1]
	v_pk_fma_f32 v[42:43], v[202:203], v[228:229], v[42:43] op_sel:[0,1,0] op_sel_hi:[1,1,1]
	v_pk_mul_f32 v[44:45], v[44:45], v[128:129] op_sel:[0,1] op_sel_hi:[1,1]
	v_pk_mul_f32 v[46:47], v[46:47], v[128:129] op_sel:[0,1] op_sel_hi:[1,1]
	v_pk_fma_f32 v[44:45], v[204:205], v[228:229], v[44:45] op_sel:[0,1,0] op_sel_hi:[1,1,1]
	v_pk_fma_f32 v[46:47], v[206:207], v[228:229], v[46:47] op_sel:[0,1,0] op_sel_hi:[1,1,1]
	v_pk_mul_f32 v[242:243], v[216:217], v[40:41]
	v_pk_fma_f32 v[242:243], v[218:219], v[42:43], v[242:243]
	v_pk_fma_f32 v[242:243], v[220:221], v[44:45], v[242:243]
	v_pk_fma_f32 v[242:243], v[222:223], v[46:47], v[242:243]
	v_add_f32_e32 v237, v242, v243
	v_pk_mul_f32 v[48:49], v[48:49], v[128:129] op_sel:[0,1] op_sel_hi:[1,1]
; __device__ __forceinline__ float bf2f(unsigned h) { return __uint_as_float(h << 16); }
; __device__ __forceinline__ unsigned f2bf(float f) { unsigned u = __float_as_uint(f); return (u + 0x7fffu + ((u >> 16) & 1u)) >> 16; }
; #define BFLY(o) do { const bool up = (nl & (o)) != 0; _Pragma("unroll") for (int i = 0; i < (o); ++i) { \
;                     const float send = up ? part[i] : part[i + (o)]; const float keep = up ? part[i + (o)] : part[i]; part[i] = keep + __shfl_xor(send, (o)); } } while (0)
; __device__ __forceinline__ void ssd_sample_items(LAS unsigned char* lds, int it0, int itstride, int nitems, const bf16_t* XBC, const float* DT, const float* a_log,
;                                                  const float* state_in, bf16_t* MIX, float* s_ssm) {
;     ...
;             for (int t = 0; t < 4; ++t) {
;                 const float dt = dtv[t]; const float da = __expf(dt * A);
;                 const f32x4 Bt = (f32x4){bf2f(Bp[t].x & 0xffffu), bf2f(Bp[t].x >> 16), bf2f(Bp[t].y & 0xffffu), bf2f(Bp[t].y >> 16)} * dt;
;                 const f32x4 Ct = (f32x4){bf2f(Cp[t].x & 0xffffu), bf2f(Cp[t].x >> 16), bf2f(Cp[t].y & 0xffffu), bf2f(Cp[t].y >> 16)};
;                 float part[8];
;                 { const bool up8 = (nl & 8) != 0;
; #pragma unroll
;                   for (int i = 0; i < 8; ++i) {
;                     const float x0 = Xs[t * 512 + w * 64 + 32 * hh + 2 * i + half], x1 = Xs[t * 512 + w * 64 + 32 * hh + 2 * (i + 8) + half];
;                     st[i] = st[i] * da + Bt * x0; st[i + 8] = st[i + 8] * da + Bt * x1;
;                     const f32x4 q0 = Ct * st[i], q1 = Ct * st[i + 8];
;                     const float p0 = (q0.x + q0.y) + (q0.z + q0.w), p1 = (q1.x + q1.y) + (q1.z + q1.w);
;                     const float send = up8 ? p0 : p1, keep = up8 ? p1 : p0; part[i] = keep + __shfl_xor(send, 8); } }
;     ...
;                 BFLY(4); BFLY(2); BFLY(1);
;     ...
;                 yv[t] = part[0] + __shfl_xor(part[0], 16);
;             }
;             const int pout = 32 * hh + 2 * (nl & 15) + half;
;             if ((nl & 16) == 0) {
; #pragma unroll
;                 for (int t = 0; t < 4; ++t) MIX[(size_t)(MP + 4 * b + t) * DMIX + h * 64 + pout] = (bf16_t)f2bf(yv[t]);
;             }
	v_pk_mul_f32 v[50:51], v[50:51], v[128:129] op_sel:[0,1] op_sel_hi:[1,1]
	v_pk_fma_f32 v[48:49], v[200:201], v[230:231], v[48:49] op_sel:[0,0,0] op_sel_hi:[1,0,1]
	v_pk_fma_f32 v[50:51], v[202:203], v[230:231], v[50:51] op_sel:[0,0,0] op_sel_hi:[1,0,1]
	v_pk_mul_f32 v[52:53], v[52:53], v[128:129] op_sel:[0,1] op_sel_hi:[1,1]
	v_pk_mul_f32 v[54:55], v[54:55], v[128:129] op_sel:[0,1] op_sel_hi:[1,1]
	v_pk_fma_f32 v[52:53], v[204:205], v[230:231], v[52:53] op_sel:[0,0,0] op_sel_hi:[1,0,1]
	v_pk_fma_f32 v[54:55], v[206:207], v[230:231], v[54:55] op_sel:[0,0,0] op_sel_hi:[1,0,1]
	v_pk_mul_f32 v[244:245], v[216:217], v[48:49]
	v_pk_fma_f32 v[244:245], v[218:219], v[50:51], v[244:245]
	v_pk_fma_f32 v[244:245], v[220:221], v[52:53], v[244:245]
	v_pk_fma_f32 v[244:245], v[222:223], v[54:55], v[244:245]
	v_add_f32_e32 v238, v244, v245
	v_pk_mul_f32 v[56:57], v[56:57], v[128:129] op_sel:[0,1] op_sel_hi:[1,1]
	v_pk_mul_f32 v[58:59], v[58:59], v[128:129] op_sel:[0,1] op_sel_hi:[1,1]
	v_pk_fma_f32 v[56:57], v[200:201], v[230:231], v[56:57] op_sel:[0,1,0] op_sel_hi:[1,1,1]
	v_pk_fma_f32 v[58:59], v[202:203], v[230:231], v[58:59] op_sel:[0,1,0] op_sel_hi:[1,1,1]
	v_pk_mul_f32 v[60:61], v[60:61], v[128:129] op_sel:[0,1] op_sel_hi:[1,1]
	v_pk_mul_f32 v[62:63], v[62:63], v[128:129] op_sel:[0,1] op_sel_hi:[1,1]
	v_pk_fma_f32 v[60:61], v[204:205], v[230:231], v[60:61] op_sel:[0,1,0] op_sel_hi:[1,1,1]
	v_pk_fma_f32 v[62:63], v[206:207], v[230:231], v[62:63] op_sel:[0,1,0] op_sel_hi:[1,1,1]
	v_pk_mul_f32 v[246:247], v[216:217], v[56:57]
	v_pk_fma_f32 v[246:247], v[218:219], v[58:59], v[246:247]
	v_pk_fma_f32 v[246:247], v[220:221], v[60:61], v[246:247]
	v_pk_fma_f32 v[246:247], v[222:223], v[62:63], v[246:247]
	v_add_f32_e32 v239, v246, v247
	v_add_f32_dpp v232, v232, v232 row_mirror row_mask:0xf bank_mask:0x3
	v_add_f32_dpp v232, v236, v236 row_mirror row_mask:0xf bank_mask:0xc
	v_add_f32_dpp v233, v233, v233 row_mirror row_mask:0xf bank_mask:0x3
	v_add_f32_dpp v233, v237, v237 row_mirror row_mask:0xf bank_mask:0xc
	v_add_f32_dpp v234, v234, v234 row_mirror row_mask:0xf bank_mask:0x3
	v_add_f32_dpp v234, v238, v238 row_mirror row_mask:0xf bank_mask:0xc
	v_add_f32_dpp v235, v235, v235 row_mirror row_mask:0xf bank_mask:0x3
	v_add_f32_dpp v235, v239, v239 row_mirror row_mask:0xf bank_mask:0xc
	v_add_f32_dpp v232, v232, v232 row_half_mirror row_mask:0xf bank_mask:0x5
	v_add_f32_dpp v232, v234, v234 row_half_mirror row_mask:0xf bank_mask:0xa
	v_add_f32_dpp v233, v233, v233 row_half_mirror row_mask:0xf bank_mask:0x5
	v_add_f32_dpp v233, v235, v235 row_half_mirror row_mask:0xf bank_mask:0xa
	v_add_f32_dpp v248, v232, v232 quad_perm:[2,3,0,1] row_mask:0xf bank_mask:0xf
	s_nop 0
	v_add_f32_dpp v249, v233, v233 quad_perm:[2,3,0,1] row_mask:0xf bank_mask:0xf
	v_cndmask_b32_e64 v232, v248, v249, s[68:69]
	s_nop 1
	v_add_f32_dpp v233, v232, v232 quad_perm:[1,0,3,2] row_mask:0xf bank_mask:0xf
	v_cvt_pk_bf16_f32 v214, v233, v233
	s_mov_b64 exec, s[38:39]
	global_store_short v213, v214, s[6:7] offset:0
	s_mov_b64 exec, -1
	v_lshlrev_b32_e32 v224, 16, v176
	v_and_b32_e32 v225, 0xffff0000, v176
	v_lshlrev_b32_e32 v226, 16, v177
	v_and_b32_e32 v227, 0xffff0000, v177
	v_lshlrev_b32_e32 v228, 16, v178
	v_and_b32_e32 v229, 0xffff0000, v178
	v_lshlrev_b32_e32 v230, 16, v179
	v_and_b32_e32 v231, 0xffff0000, v179
	v_lshlrev_b32_e32 v200, 16, v144
	v_and_b32_e32 v201, 0xffff0000, v144
	v_lshlrev_b32_e32 v202, 16, v145
	v_and_b32_e32 v203, 0xffff0000, v145
	v_lshlrev_b32_e32 v204, 16, v146
	v_and_b32_e32 v205, 0xffff0000, v146
	v_lshlrev_b32_e32 v206, 16, v147
	v_and_b32_e32 v207, 0xffff0000, v147
	v_lshlrev_b32_e32 v216, 16, v160
	v_and_b32_e32 v217, 0xffff0000, v160
	v_lshlrev_b32_e32 v218, 16, v161
	v_and_b32_e32 v219, 0xffff0000, v161
	v_lshlrev_b32_e32 v220, 16, v162
	v_and_b32_e32 v221, 0xffff0000, v162
	v_lshlrev_b32_e32 v222, 16, v163
	v_and_b32_e32 v223, 0xffff0000, v163
	v_pk_mul_f32 v[200:201], v[200:201], v[210:211] op_sel:[0,0] op_sel_hi:[1,0]
	v_pk_mul_f32 v[202:203], v[202:203], v[210:211] op_sel:[0,0] op_sel_hi:[1,0]
	v_pk_mul_f32 v[204:205], v[204:205], v[210:211] op_sel:[0,0] op_sel_hi:[1,0]
	v_pk_mul_f32 v[206:207], v[206:207], v[210:211] op_sel:[0,0] op_sel_hi:[1,0]
	v_pk_mul_f32 v[0:1], v[0:1], v[130:131] op_sel:[0,0] op_sel_hi:[1,0]
	v_pk_mul_f32 v[2:3], v[2:3], v[130:131] op_sel:[0,0] op_sel_hi:[1,0]
	v_pk_fma_f32 v[0:1], v[200:201], v[224:225], v[0:1] op_sel:[0,0,0] op_sel_hi:[1,0,1]
	v_pk_fma_f32 v[2:3], v[202:203], v[224:225], v[2:3] op_sel:[0,0,0] op_sel_hi:[1,0,1]
	v_pk_mul_f32 v[4:5], v[4:5], v[130:131] op_sel:[0,0] op_sel_hi:[1,0]
	v_pk_mul_f32 v[6:7], v[6:7], v[130:131] op_sel:[0,0] op_sel_hi:[1,0]
	v_pk_fma_f32 v[4:5], v[204:205], v[224:225], v[4:5] op_sel:[0,0,0] op_sel_hi:[1,0,1]
	v_pk_fma_f32 v[6:7], v[206:207], v[224:225], v[6:7] op_sel:[0,0,0] op_sel_hi:[1,0,1]
	v_pk_mul_f32 v[240:241], v[216:217], v[0:1]
	v_pk_fma_f32 v[240:241], v[218:219], v[2:3], v[240:241]
	v_pk_fma_f32 v[240:241], v[220:221], v[4:5], v[240:241]
	v_pk_fma_f32 v[240:241], v[222:223], v[6:7], v[240:241]
	v_add_f32_e32 v232, v240, v241
	v_pk_mul_f32 v[8:9], v[8:9], v[130:131] op_sel:[0,0] op_sel_hi:[1,0]
	v_pk_mul_f32 v[10:11], v[10:11], v[130:131] op_sel:[0,0] op_sel_hi:[1,0]
	v_pk_fma_f32 v[8:9], v[200:201], v[224:225], v[8:9] op_sel:[0,1,0] op_sel_hi:[1,1,1]
	v_pk_fma_f32 v[10:11], v[202:203], v[224:225], v[10:11] op_sel:[0,1,0] op_sel_hi:[1,1,1]
	v_pk_mul_f32 v[12:13], v[12:13], v[130:131] op_sel:[0,0] op_sel_hi:[1,0]
	v_pk_mul_f32 v[14:15], v[14:15], v[130:131] op_sel:[0,0] op_sel_hi:[1,0]
	v_pk_fma_f32 v[12:13], v[204:205], v[224:225], v[12:13] op_sel:[0,1,0] op_sel_hi:[1,1,1]
; __device__ __forceinline__ float bf2f(unsigned h) { return __uint_as_float(h << 16); }
; __device__ __forceinline__ void ssd_sample_items(LAS unsigned char* lds, int it0, int itstride, int nitems, const bf16_t* XBC, const float* DT, const float* a_log,
;                                                  const float* state_in, bf16_t* MIX, float* s_ssm) {
;     ...
;             for (int t = 0; t < 4; ++t) {
;                 const float dt = dtv[t]; const float da = __expf(dt * A);
;                 const f32x4 Bt = (f32x4){bf2f(Bp[t].x & 0xffffu), bf2f(Bp[t].x >> 16), bf2f(Bp[t].y & 0xffffu), bf2f(Bp[t].y >> 16)} * dt;
;                 const f32x4 Ct = (f32x4){bf2f(Cp[t].x & 0xffffu), bf2f(Cp[t].x >> 16), bf2f(Cp[t].y & 0xffffu), bf2f(Cp[t].y >> 16)};
;                 float part[8];
;                 { const bool up8 = (nl & 8) != 0;
; #pragma unroll
;                   for (int i = 0; i < 8; ++i) {
;                     const float x0 = Xs[t * 512 + w * 64 + 32 * hh + 2 * i + half], x1 = Xs[t * 512 + w * 64 + 32 * hh + 2 * (i + 8) + half];
;                     st[i] = st[i] * da + Bt * x0; st[i + 8] = st[i + 8] * da + Bt * x1;
;                     const f32x4 q0 = Ct * st[i], q1 = Ct * st[i + 8];
;                     const float p0 = (q0.x + q0.y) + (q0.z + q0.w), p1 = (q1.x + q1.y) + (q1.z + q1.w);
;                     const float send = up8 ? p0 : p1, keep = up8 ? p1 : p0; part[i] = keep + __shfl_xor(send, 8); } }
	v_pk_fma_f32 v[14:15], v[206:207], v[224:225], v[14:15] op_sel:[0,1,0] op_sel_hi:[1,1,1]
	v_pk_mul_f32 v[242:243], v[216:217], v[8:9]
	v_pk_fma_f32 v[242:243], v[218:219], v[10:11], v[242:243]
	v_pk_fma_f32 v[242:243], v[220:221], v[12:13], v[242:243]
	v_pk_fma_f32 v[242:243], v[222:223], v[14:15], v[242:243]
	v_add_f32_e32 v233, v242, v243
	v_pk_mul_f32 v[16:17], v[16:17], v[130:131] op_sel:[0,0] op_sel_hi:[1,0]
	v_pk_mul_f32 v[18:19], v[18:19], v[130:131] op_sel:[0,0] op_sel_hi:[1,0]
	v_pk_fma_f32 v[16:17], v[200:201], v[226:227], v[16:17] op_sel:[0,0,0] op_sel_hi:[1,0,1]
	v_pk_fma_f32 v[18:19], v[202:203], v[226:227], v[18:19] op_sel:[0,0,0] op_sel_hi:[1,0,1]
	v_pk_mul_f32 v[20:21], v[20:21], v[130:131] op_sel:[0,0] op_sel_hi:[1,0]
	v_pk_mul_f32 v[22:23], v[22:23], v[130:131] op_sel:[0,0] op_sel_hi:[1,0]
	v_pk_fma_f32 v[20:21], v[204:205], v[226:227], v[20:21] op_sel:[0,0,0] op_sel_hi:[1,0,1]
	v_pk_fma_f32 v[22:23], v[206:207], v[226:227], v[22:23] op_sel:[0,0,0] op_sel_hi:[1,0,1]
	v_pk_mul_f32 v[244:245], v[216:217], v[16:17]
	v_pk_fma_f32 v[244:245], v[218:219], v[18:19], v[244:245]
	v_pk_fma_f32 v[244:245], v[220:221], v[20:21], v[244:245]
	v_pk_fma_f32 v[244:245], v[222:223], v[22:23], v[244:245]
	v_add_f32_e32 v234, v244, v245
	v_pk_mul_f32 v[24:25], v[24:25], v[130:131] op_sel:[0,0] op_sel_hi:[1,0]
	v_pk_mul_f32 v[26:27], v[26:27], v[130:131] op_sel:[0,0] op_sel_hi:[1,0]
	v_pk_fma_f32 v[24:25], v[200:201], v[226:227], v[24:25] op_sel:[0,1,0] op_sel_hi:[1,1,1]
	v_pk_fma_f32 v[26:27], v[202:203], v[226:227], v[26:27] op_sel:[0,1,0] op_sel_hi:[1,1,1]
	v_pk_mul_f32 v[28:29], v[28:29], v[130:131] op_sel:[0,0] op_sel_hi:[1,0]
	v_pk_mul_f32 v[30:31], v[30:31], v[130:131] op_sel:[0,0] op_sel_hi:[1,0]
	v_pk_fma_f32 v[28:29], v[204:205], v[226:227], v[28:29] op_sel:[0,1,0] op_sel_hi:[1,1,1]
	v_pk_fma_f32 v[30:31], v[206:207], v[226:227], v[30:31] op_sel:[0,1,0] op_sel_hi:[1,1,1]
	v_pk_mul_f32 v[246:247], v[216:217], v[24:25]
	v_pk_fma_f32 v[246:247], v[218:219], v[26:27], v[246:247]
	v_pk_fma_f32 v[246:247], v[220:221], v[28:29], v[246:247]
	v_pk_fma_f32 v[246:247], v[222:223], v[30:31], v[246:247]
	v_add_f32_e32 v235, v246, v247
	v_pk_mul_f32 v[32:33], v[32:33], v[130:131] op_sel:[0,0] op_sel_hi:[1,0]
	v_pk_mul_f32 v[34:35], v[34:35], v[130:131] op_sel:[0,0] op_sel_hi:[1,0]
	v_pk_fma_f32 v[32:33], v[200:201], v[228:229], v[32:33] op_sel:[0,0,0] op_sel_hi:[1,0,1]
	v_pk_fma_f32 v[34:35], v[202:203], v[228:229], v[34:35] op_sel:[0,0,0] op_sel_hi:[1,0,1]
	v_pk_mul_f32 v[36:37], v[36:37], v[130:131] op_sel:[0,0] op_sel_hi:[1,0]
	v_pk_mul_f32 v[38:39], v[38:39], v[130:131] op_sel:[0,0] op_sel_hi:[1,0]
	v_pk_fma_f32 v[36:37], v[204:205], v[228:229], v[36:37] op_sel:[0,0,0] op_sel_hi:[1,0,1]
	v_pk_fma_f32 v[38:39], v[206:207], v[228:229], v[38:39] op_sel:[0,0,0] op_sel_hi:[1,0,1]
	v_pk_mul_f32 v[240:241], v[216:217], v[32:33]
	v_pk_fma_f32 v[240:241], v[218:219], v[34:35], v[240:241]
	v_pk_fma_f32 v[240:241], v[220:221], v[36:37], v[240:241]
	v_pk_fma_f32 v[240:241], v[222:223], v[38:39], v[240:241]
	v_add_f32_e32 v236, v240, v241
	v_pk_mul_f32 v[40:41], v[40:41], v[130:131] op_sel:[0,0] op_sel_hi:[1,0]
	v_pk_mul_f32 v[42:43], v[42:43], v[130:131] op_sel:[0,0] op_sel_hi:[1,0]
	v_pk_fma_f32 v[40:41], v[200:201], v[228:229], v[40:41] op_sel:[0,1,0] op_sel_hi:[1,1,1]
	v_pk_fma_f32 v[42:43], v[202:203], v[228:229], v[42:43] op_sel:[0,1,0] op_sel_hi:[1,1,1]
	v_pk_mul_f32 v[44:45], v[44:45], v[130:131] op_sel:[0,0] op_sel_hi:[1,0]
	v_pk_mul_f32 v[46:47], v[46:47], v[130:131] op_sel:[0,0] op_sel_hi:[1,0]
	v_pk_fma_f32 v[44:45], v[204:205], v[228:229], v[44:45] op_sel:[0,1,0] op_sel_hi:[1,1,1]
	v_pk_fma_f32 v[46:47], v[206:207], v[228:229], v[46:47] op_sel:[0,1,0] op_sel_hi:[1,1,1]
	v_pk_mul_f32 v[242:243], v[216:217], v[40:41]
	v_pk_fma_f32 v[242:243], v[218:219], v[42:43], v[242:243]
	v_pk_fma_f32 v[242:243], v[220:221], v[44:45], v[242:243]
	v_pk_fma_f32 v[242:243], v[222:223], v[46:47], v[242:243]
	v_add_f32_e32 v237, v242, v243
	v_pk_mul_f32 v[48:49], v[48:49], v[130:131] op_sel:[0,0] op_sel_hi:[1,0]
	v_pk_mul_f32 v[50:51], v[50:51], v[130:131] op_sel:[0,0] op_sel_hi:[1,0]
	v_pk_fma_f32 v[48:49], v[200:201], v[230:231], v[48:49] op_sel:[0,0,0] op_sel_hi:[1,0,1]
	v_pk_fma_f32 v[50:51], v[202:203], v[230:231], v[50:51] op_sel:[0,0,0] op_sel_hi:[1,0,1]
	v_pk_mul_f32 v[52:53], v[52:53], v[130:131] op_sel:[0,0] op_sel_hi:[1,0]
	v_pk_mul_f32 v[54:55], v[54:55], v[130:131] op_sel:[0,0] op_sel_hi:[1,0]
	v_pk_fma_f32 v[52:53], v[204:205], v[230:231], v[52:53] op_sel:[0,0,0] op_sel_hi:[1,0,1]
	v_pk_fma_f32 v[54:55], v[206:207], v[230:231], v[54:55] op_sel:[0,0,0] op_sel_hi:[1,0,1]
	v_pk_mul_f32 v[244:245], v[216:217], v[48:49]
	v_pk_fma_f32 v[244:245], v[218:219], v[50:51], v[244:245]
	v_pk_fma_f32 v[244:245], v[220:221], v[52:53], v[244:245]
	v_pk_fma_f32 v[244:245], v[222:223], v[54:55], v[244:245]
	v_add_f32_e32 v238, v244, v245
	v_pk_mul_f32 v[56:57], v[56:57], v[130:131] op_sel:[0,0] op_sel_hi:[1,0]
	v_pk_mul_f32 v[58:59], v[58:59], v[130:131] op_sel:[0,0] op_sel_hi:[1,0]
	v_pk_fma_f32 v[56:57], v[200:201], v[230:231], v[56:57] op_sel:[0,1,0] op_sel_hi:[1,1,1]
	v_pk_fma_f32 v[58:59], v[202:203], v[230:231], v[58:59] op_sel:[0,1,0] op_sel_hi:[1,1,1]
	v_pk_mul_f32 v[60:61], v[60:61], v[130:131] op_sel:[0,0] op_sel_hi:[1,0]
	v_pk_mul_f32 v[62:63], v[62:63], v[130:131] op_sel:[0,0] op_sel_hi:[1,0]
	v_pk_fma_f32 v[60:61], v[204:205], v[230:231], v[60:61] op_sel:[0,1,0] op_sel_hi:[1,1,1]
	v_pk_fma_f32 v[62:63], v[206:207], v[230:231], v[62:63] op_sel:[0,1,0] op_sel_hi:[1,1,1]
	v_pk_mul_f32 v[246:247], v[216:217], v[56:57]
	v_pk_fma_f32 v[246:247], v[218:219], v[58:59], v[246:247]
; __device__ __forceinline__ float bf2f(unsigned h) { return __uint_as_float(h << 16); }
; __device__ __forceinline__ unsigned f2bf(float f) { unsigned u = __float_as_uint(f); return (u + 0x7fffu + ((u >> 16) & 1u)) >> 16; }
; #define BFLY(o) do { const bool up = (nl & (o)) != 0; _Pragma("unroll") for (int i = 0; i < (o); ++i) { \
;                     const float send = up ? part[i] : part[i + (o)]; const float keep = up ? part[i + (o)] : part[i]; part[i] = keep + __shfl_xor(send, (o)); } } while (0)
; __device__ __forceinline__ void ssd_sample_items(LAS unsigned char* lds, int it0, int itstride, int nitems, const bf16_t* XBC, const float* DT, const float* a_log,
;                                                  const float* state_in, bf16_t* MIX, float* s_ssm) {
;     ...
;             for (int t = 0; t < 4; ++t) {
;                 const float dt = dtv[t]; const float da = __expf(dt * A);
;                 const f32x4 Bt = (f32x4){bf2f(Bp[t].x & 0xffffu), bf2f(Bp[t].x >> 16), bf2f(Bp[t].y & 0xffffu), bf2f(Bp[t].y >> 16)} * dt;
;                 const f32x4 Ct = (f32x4){bf2f(Cp[t].x & 0xffffu), bf2f(Cp[t].x >> 16), bf2f(Cp[t].y & 0xffffu), bf2f(Cp[t].y >> 16)};
;                 float part[8];
;                 { const bool up8 = (nl & 8) != 0;
; #pragma unroll
;                   for (int i = 0; i < 8; ++i) {
;                     const float x0 = Xs[t * 512 + w * 64 + 32 * hh + 2 * i + half], x1 = Xs[t * 512 + w * 64 + 32 * hh + 2 * (i + 8) + half];
;                     st[i] = st[i] * da + Bt * x0; st[i + 8] = st[i + 8] * da + Bt * x1;
;                     const f32x4 q0 = Ct * st[i], q1 = Ct * st[i + 8];
;                     const float p0 = (q0.x + q0.y) + (q0.z + q0.w), p1 = (q1.x + q1.y) + (q1.z + q1.w);
;                     const float send = up8 ? p0 : p1, keep = up8 ? p1 : p0; part[i] = keep + __shfl_xor(send, 8); } }
;     ...
;                 BFLY(4); BFLY(2); BFLY(1);
;     ...
;                 yv[t] = part[0] + __shfl_xor(part[0], 16);
;             }
;             const int pout = 32 * hh + 2 * (nl & 15) + half;
;             if ((nl & 16) == 0) {
; #pragma unroll
;                 for (int t = 0; t < 4; ++t) MIX[(size_t)(MP + 4 * b + t) * DMIX + h * 64 + pout] = (bf16_t)f2bf(yv[t]);
;             }
	v_pk_fma_f32 v[246:247], v[220:221], v[60:61], v[246:247]
	v_pk_fma_f32 v[246:247], v[222:223], v[62:63], v[246:247]
	v_add_f32_e32 v239, v246, v247
	v_add_f32_dpp v232, v232, v232 row_mirror row_mask:0xf bank_mask:0x3
	v_add_f32_dpp v232, v236, v236 row_mirror row_mask:0xf bank_mask:0xc
	v_add_f32_dpp v233, v233, v233 row_mirror row_mask:0xf bank_mask:0x3
	v_add_f32_dpp v233, v237, v237 row_mirror row_mask:0xf bank_mask:0xc
	v_add_f32_dpp v234, v234, v234 row_mirror row_mask:0xf bank_mask:0x3
	v_add_f32_dpp v234, v238, v238 row_mirror row_mask:0xf bank_mask:0xc
	v_add_f32_dpp v235, v235, v235 row_mirror row_mask:0xf bank_mask:0x3
	v_add_f32_dpp v235, v239, v239 row_mirror row_mask:0xf bank_mask:0xc
	v_add_f32_dpp v232, v232, v232 row_half_mirror row_mask:0xf bank_mask:0x5
	v_add_f32_dpp v232, v234, v234 row_half_mirror row_mask:0xf bank_mask:0xa
	v_add_f32_dpp v233, v233, v233 row_half_mirror row_mask:0xf bank_mask:0x5
	v_add_f32_dpp v233, v235, v235 row_half_mirror row_mask:0xf bank_mask:0xa
	v_add_f32_dpp v248, v232, v232 quad_perm:[2,3,0,1] row_mask:0xf bank_mask:0xf
	s_nop 0
	v_add_f32_dpp v249, v233, v233 quad_perm:[2,3,0,1] row_mask:0xf bank_mask:0xf
	v_cndmask_b32_e64 v232, v248, v249, s[68:69]
	s_nop 1
	v_add_f32_dpp v233, v232, v232 quad_perm:[1,0,3,2] row_mask:0xf bank_mask:0xf
	v_cvt_pk_bf16_f32 v214, v233, v233
	s_mov_b64 exec, s[38:39]
	global_store_short v213, v214, s[8:9] offset:0
	s_mov_b64 exec, -1
	v_lshlrev_b32_e32 v224, 16, v180
	v_and_b32_e32 v225, 0xffff0000, v180
	v_lshlrev_b32_e32 v226, 16, v181
	v_and_b32_e32 v227, 0xffff0000, v181
	v_lshlrev_b32_e32 v228, 16, v182
	v_and_b32_e32 v229, 0xffff0000, v182
	v_lshlrev_b32_e32 v230, 16, v183
	v_and_b32_e32 v231, 0xffff0000, v183
	v_lshlrev_b32_e32 v200, 16, v148
	v_and_b32_e32 v201, 0xffff0000, v148
	v_lshlrev_b32_e32 v202, 16, v149
	v_and_b32_e32 v203, 0xffff0000, v149
	v_lshlrev_b32_e32 v204, 16, v150
	v_and_b32_e32 v205, 0xffff0000, v150
	v_lshlrev_b32_e32 v206, 16, v151
	v_and_b32_e32 v207, 0xffff0000, v151
	v_lshlrev_b32_e32 v216, 16, v164
	v_and_b32_e32 v217, 0xffff0000, v164
	v_lshlrev_b32_e32 v218, 16, v165
	v_and_b32_e32 v219, 0xffff0000, v165
	v_lshlrev_b32_e32 v220, 16, v166
	v_and_b32_e32 v221, 0xffff0000, v166
	v_lshlrev_b32_e32 v222, 16, v167
	v_and_b32_e32 v223, 0xffff0000, v167
	v_pk_mul_f32 v[200:201], v[200:201], v[210:211] op_sel:[0,1] op_sel_hi:[1,1]
	v_pk_mul_f32 v[202:203], v[202:203], v[210:211] op_sel:[0,1] op_sel_hi:[1,1]
	v_pk_mul_f32 v[204:205], v[204:205], v[210:211] op_sel:[0,1] op_sel_hi:[1,1]
	v_pk_mul_f32 v[206:207], v[206:207], v[210:211] op_sel:[0,1] op_sel_hi:[1,1]
	v_pk_mul_f32 v[0:1], v[0:1], v[130:131] op_sel:[0,1] op_sel_hi:[1,1]
	v_pk_mul_f32 v[2:3], v[2:3], v[130:131] op_sel:[0,1] op_sel_hi:[1,1]
	v_pk_fma_f32 v[0:1], v[200:201], v[224:225], v[0:1] op_sel:[0,0,0] op_sel_hi:[1,0,1]
	v_pk_fma_f32 v[2:3], v[202:203], v[224:225], v[2:3] op_sel:[0,0,0] op_sel_hi:[1,0,1]
	v_pk_mul_f32 v[4:5], v[4:5], v[130:131] op_sel:[0,1] op_sel_hi:[1,1]
	v_pk_mul_f32 v[6:7], v[6:7], v[130:131] op_sel:[0,1] op_sel_hi:[1,1]
	v_pk_fma_f32 v[4:5], v[204:205], v[224:225], v[4:5] op_sel:[0,0,0] op_sel_hi:[1,0,1]
	v_pk_fma_f32 v[6:7], v[206:207], v[224:225], v[6:7] op_sel:[0,0,0] op_sel_hi:[1,0,1]
	v_pk_mul_f32 v[240:241], v[216:217], v[0:1]
	v_pk_fma_f32 v[240:241], v[218:219], v[2:3], v[240:241]
	v_pk_fma_f32 v[240:241], v[220:221], v[4:5], v[240:241]
	v_pk_fma_f32 v[240:241], v[222:223], v[6:7], v[240:241]
	v_add_f32_e32 v232, v240, v241
	v_pk_mul_f32 v[8:9], v[8:9], v[130:131] op_sel:[0,1] op_sel_hi:[1,1]
	v_pk_mul_f32 v[10:11], v[10:11], v[130:131] op_sel:[0,1] op_sel_hi:[1,1]
	v_pk_fma_f32 v[8:9], v[200:201], v[224:225], v[8:9] op_sel:[0,1,0] op_sel_hi:[1,1,1]
	v_pk_fma_f32 v[10:11], v[202:203], v[224:225], v[10:11] op_sel:[0,1,0] op_sel_hi:[1,1,1]
	v_pk_mul_f32 v[12:13], v[12:13], v[130:131] op_sel:[0,1] op_sel_hi:[1,1]
	v_pk_mul_f32 v[14:15], v[14:15], v[130:131] op_sel:[0,1] op_sel_hi:[1,1]
	v_pk_fma_f32 v[12:13], v[204:205], v[224:225], v[12:13] op_sel:[0,1,0] op_sel_hi:[1,1,1]
	v_pk_fma_f32 v[14:15], v[206:207], v[224:225], v[14:15] op_sel:[0,1,0] op_sel_hi:[1,1,1]
	v_pk_mul_f32 v[242:243], v[216:217], v[8:9]
	v_pk_fma_f32 v[242:243], v[218:219], v[10:11], v[242:243]
	v_pk_fma_f32 v[242:243], v[220:221], v[12:13], v[242:243]
	v_pk_fma_f32 v[242:243], v[222:223], v[14:15], v[242:243]
	v_add_f32_e32 v233, v242, v243
	v_pk_mul_f32 v[16:17], v[16:17], v[130:131] op_sel:[0,1] op_sel_hi:[1,1]
	v_pk_mul_f32 v[18:19], v[18:19], v[130:131] op_sel:[0,1] op_sel_hi:[1,1]
	v_pk_fma_f32 v[16:17], v[200:201], v[226:227], v[16:17] op_sel:[0,0,0] op_sel_hi:[1,0,1]
	v_pk_fma_f32 v[18:19], v[202:203], v[226:227], v[18:19] op_sel:[0,0,0] op_sel_hi:[1,0,1]
	v_pk_mul_f32 v[20:21], v[20:21], v[130:131] op_sel:[0,1] op_sel_hi:[1,1]
	v_pk_mul_f32 v[22:23], v[22:23], v[130:131] op_sel:[0,1] op_sel_hi:[1,1]
	v_pk_fma_f32 v[20:21], v[204:205], v[226:227], v[20:21] op_sel:[0,0,0] op_sel_hi:[1,0,1]
	v_pk_fma_f32 v[22:23], v[206:207], v[226:227], v[22:23] op_sel:[0,0,0] op_sel_hi:[1,0,1]
	v_pk_mul_f32 v[244:245], v[216:217], v[16:17]
	v_pk_fma_f32 v[244:245], v[218:219], v[18:19], v[244:245]
	v_pk_fma_f32 v[244:245], v[220:221], v[20:21], v[244:245]
	v_pk_fma_f32 v[244:245], v[222:223], v[22:23], v[244:245]
	v_add_f32_e32 v234, v244, v245
	v_pk_mul_f32 v[24:25], v[24:25], v[130:131] op_sel:[0,1] op_sel_hi:[1,1]
	v_pk_mul_f32 v[26:27], v[26:27], v[130:131] op_sel:[0,1] op_sel_hi:[1,1]
	v_pk_fma_f32 v[24:25], v[200:201], v[226:227], v[24:25] op_sel:[0,1,0] op_sel_hi:[1,1,1]
	v_pk_fma_f32 v[26:27], v[202:203], v[226:227], v[26:27] op_sel:[0,1,0] op_sel_hi:[1,1,1]
; __device__ __forceinline__ void ssd_sample_items(LAS unsigned char* lds, int it0, int itstride, int nitems, const bf16_t* XBC, const float* DT, const float* a_log,
;                                                  const float* state_in, bf16_t* MIX, float* s_ssm) {
;     ...
;                 const int itn = it + itstride;
;                 if (hh == 0) { const float* sp = state_in + (size_t)(b * NH + h) * HP * NS + 4096;
; #pragma unroll
;                     for (int k = 0; k < 16; ++k) nx[k] = *(const f32x4*)(sp + k * 256 + lane * 4); }
;                 else if (itn < nitems) { const int bn = itn >> 2, gn = itn & 3; const float* sp = state_in + (size_t)(bn * NH + gn * 8 + w) * HP * NS;
; #pragma unroll
;                     for (int k = 0; k < 16; ++k) nx[k] = *(const f32x4*)(sp + k * 256 + lane * 4); }
;             }
;             float yv[4];
; #pragma unroll
;             for (int t = 0; t < 4; ++t) {
;                 const float dt = dtv[t]; const float da = __expf(dt * A);
;                 const f32x4 Bt = (f32x4){bf2f(Bp[t].x & 0xffffu), bf2f(Bp[t].x >> 16), bf2f(Bp[t].y & 0xffffu), bf2f(Bp[t].y >> 16)} * dt;
;                 const f32x4 Ct = (f32x4){bf2f(Cp[t].x & 0xffffu), bf2f(Cp[t].x >> 16), bf2f(Cp[t].y & 0xffffu), bf2f(Cp[t].y >> 16)};
;                 float part[8];
;                 { const bool up8 = (nl & 8) != 0;
; #pragma unroll
;                   for (int i = 0; i < 8; ++i) {
;                     const float x0 = Xs[t * 512 + w * 64 + 32 * hh + 2 * i + half], x1 = Xs[t * 512 + w * 64 + 32 * hh + 2 * (i + 8) + half];
;                     st[i] = st[i] * da + Bt * x0; st[i + 8] = st[i + 8] * da + Bt * x1;
;                     const f32x4 q0 = Ct * st[i], q1 = Ct * st[i + 8];
;                     const float p0 = (q0.x + q0.y) + (q0.z + q0.w), p1 = (q1.x + q1.y) + (q1.z + q1.w);
;                     const float send = up8 ? p0 : p1, keep = up8 ? p1 : p0; part[i] = keep + __shfl_xor(send, 8); } }
;     ...
;                 BFLY(4); BFLY(2); BFLY(1);
;     ...
;                 yv[t] = part[0] + __shfl_xor(part[0], 16);
;             }
;             const int pout = 32 * hh + 2 * (nl & 15) + half;
;             if ((nl & 16) == 0) {
; #pragma unroll
;                 for (int t = 0; t < 4; ++t) MIX[(size_t)(MP + 4 * b + t) * DMIX + h * 64 + pout] = (bf16_t)f2bf(yv[t]);
;             }
	v_pk_mul_f32 v[28:29], v[28:29], v[130:131] op_sel:[0,1] op_sel_hi:[1,1]
	v_pk_mul_f32 v[30:31], v[30:31], v[130:131] op_sel:[0,1] op_sel_hi:[1,1]
	v_pk_fma_f32 v[28:29], v[204:205], v[226:227], v[28:29] op_sel:[0,1,0] op_sel_hi:[1,1,1]
	v_pk_fma_f32 v[30:31], v[206:207], v[226:227], v[30:31] op_sel:[0,1,0] op_sel_hi:[1,1,1]
	v_pk_mul_f32 v[246:247], v[216:217], v[24:25]
	v_pk_fma_f32 v[246:247], v[218:219], v[26:27], v[246:247]
	v_pk_fma_f32 v[246:247], v[220:221], v[28:29], v[246:247]
	v_pk_fma_f32 v[246:247], v[222:223], v[30:31], v[246:247]
	v_add_f32_e32 v235, v246, v247
	v_pk_mul_f32 v[32:33], v[32:33], v[130:131] op_sel:[0,1] op_sel_hi:[1,1]
	v_pk_mul_f32 v[34:35], v[34:35], v[130:131] op_sel:[0,1] op_sel_hi:[1,1]
	v_pk_fma_f32 v[32:33], v[200:201], v[228:229], v[32:33] op_sel:[0,0,0] op_sel_hi:[1,0,1]
	v_pk_fma_f32 v[34:35], v[202:203], v[228:229], v[34:35] op_sel:[0,0,0] op_sel_hi:[1,0,1]
	v_pk_mul_f32 v[36:37], v[36:37], v[130:131] op_sel:[0,1] op_sel_hi:[1,1]
	v_pk_mul_f32 v[38:39], v[38:39], v[130:131] op_sel:[0,1] op_sel_hi:[1,1]
	v_pk_fma_f32 v[36:37], v[204:205], v[228:229], v[36:37] op_sel:[0,0,0] op_sel_hi:[1,0,1]
	v_pk_fma_f32 v[38:39], v[206:207], v[228:229], v[38:39] op_sel:[0,0,0] op_sel_hi:[1,0,1]
	v_pk_mul_f32 v[240:241], v[216:217], v[32:33]
	v_pk_fma_f32 v[240:241], v[218:219], v[34:35], v[240:241]
	v_pk_fma_f32 v[240:241], v[220:221], v[36:37], v[240:241]
	v_pk_fma_f32 v[240:241], v[222:223], v[38:39], v[240:241]
	v_add_f32_e32 v236, v240, v241
	v_pk_mul_f32 v[40:41], v[40:41], v[130:131] op_sel:[0,1] op_sel_hi:[1,1]
	v_pk_mul_f32 v[42:43], v[42:43], v[130:131] op_sel:[0,1] op_sel_hi:[1,1]
	v_pk_fma_f32 v[40:41], v[200:201], v[228:229], v[40:41] op_sel:[0,1,0] op_sel_hi:[1,1,1]
	v_pk_fma_f32 v[42:43], v[202:203], v[228:229], v[42:43] op_sel:[0,1,0] op_sel_hi:[1,1,1]
	v_pk_mul_f32 v[44:45], v[44:45], v[130:131] op_sel:[0,1] op_sel_hi:[1,1]
	v_pk_mul_f32 v[46:47], v[46:47], v[130:131] op_sel:[0,1] op_sel_hi:[1,1]
	v_pk_fma_f32 v[44:45], v[204:205], v[228:229], v[44:45] op_sel:[0,1,0] op_sel_hi:[1,1,1]
	v_pk_fma_f32 v[46:47], v[206:207], v[228:229], v[46:47] op_sel:[0,1,0] op_sel_hi:[1,1,1]
	v_pk_mul_f32 v[242:243], v[216:217], v[40:41]
	v_pk_fma_f32 v[242:243], v[218:219], v[42:43], v[242:243]
	v_pk_fma_f32 v[242:243], v[220:221], v[44:45], v[242:243]
	v_pk_fma_f32 v[242:243], v[222:223], v[46:47], v[242:243]
	v_add_f32_e32 v237, v242, v243
	v_pk_mul_f32 v[48:49], v[48:49], v[130:131] op_sel:[0,1] op_sel_hi:[1,1]
	v_pk_mul_f32 v[50:51], v[50:51], v[130:131] op_sel:[0,1] op_sel_hi:[1,1]
	v_pk_fma_f32 v[48:49], v[200:201], v[230:231], v[48:49] op_sel:[0,0,0] op_sel_hi:[1,0,1]
	v_pk_fma_f32 v[50:51], v[202:203], v[230:231], v[50:51] op_sel:[0,0,0] op_sel_hi:[1,0,1]
	v_pk_mul_f32 v[52:53], v[52:53], v[130:131] op_sel:[0,1] op_sel_hi:[1,1]
	v_pk_mul_f32 v[54:55], v[54:55], v[130:131] op_sel:[0,1] op_sel_hi:[1,1]
	v_pk_fma_f32 v[52:53], v[204:205], v[230:231], v[52:53] op_sel:[0,0,0] op_sel_hi:[1,0,1]
	v_pk_fma_f32 v[54:55], v[206:207], v[230:231], v[54:55] op_sel:[0,0,0] op_sel_hi:[1,0,1]
	v_pk_mul_f32 v[244:245], v[216:217], v[48:49]
	v_pk_fma_f32 v[244:245], v[218:219], v[50:51], v[244:245]
	v_pk_fma_f32 v[244:245], v[220:221], v[52:53], v[244:245]
	v_pk_fma_f32 v[244:245], v[222:223], v[54:55], v[244:245]
	v_add_f32_e32 v238, v244, v245
	v_pk_mul_f32 v[56:57], v[56:57], v[130:131] op_sel:[0,1] op_sel_hi:[1,1]
	v_pk_mul_f32 v[58:59], v[58:59], v[130:131] op_sel:[0,1] op_sel_hi:[1,1]
	v_pk_fma_f32 v[56:57], v[200:201], v[230:231], v[56:57] op_sel:[0,1,0] op_sel_hi:[1,1,1]
	v_pk_fma_f32 v[58:59], v[202:203], v[230:231], v[58:59] op_sel:[0,1,0] op_sel_hi:[1,1,1]
	v_pk_mul_f32 v[60:61], v[60:61], v[130:131] op_sel:[0,1] op_sel_hi:[1,1]
	v_pk_mul_f32 v[62:63], v[62:63], v[130:131] op_sel:[0,1] op_sel_hi:[1,1]
	v_pk_fma_f32 v[60:61], v[204:205], v[230:231], v[60:61] op_sel:[0,1,0] op_sel_hi:[1,1,1]
	v_pk_fma_f32 v[62:63], v[206:207], v[230:231], v[62:63] op_sel:[0,1,0] op_sel_hi:[1,1,1]
	v_pk_mul_f32 v[246:247], v[216:217], v[56:57]
	v_pk_fma_f32 v[246:247], v[218:219], v[58:59], v[246:247]
	v_pk_fma_f32 v[246:247], v[220:221], v[60:61], v[246:247]
	v_pk_fma_f32 v[246:247], v[222:223], v[62:63], v[246:247]
	v_add_f32_e32 v239, v246, v247
	v_add_f32_dpp v232, v232, v232 row_mirror row_mask:0xf bank_mask:0x3
	v_add_f32_dpp v232, v236, v236 row_mirror row_mask:0xf bank_mask:0xc
	v_add_f32_dpp v233, v233, v233 row_mirror row_mask:0xf bank_mask:0x3
	v_add_f32_dpp v233, v237, v237 row_mirror row_mask:0xf bank_mask:0xc
	v_add_f32_dpp v234, v234, v234 row_mirror row_mask:0xf bank_mask:0x3
	v_add_f32_dpp v234, v238, v238 row_mirror row_mask:0xf bank_mask:0xc
	v_add_f32_dpp v235, v235, v235 row_mirror row_mask:0xf bank_mask:0x3
	v_add_f32_dpp v235, v239, v239 row_mirror row_mask:0xf bank_mask:0xc
	v_add_f32_dpp v232, v232, v232 row_half_mirror row_mask:0xf bank_mask:0x5
	v_add_f32_dpp v232, v234, v234 row_half_mirror row_mask:0xf bank_mask:0xa
	v_add_f32_dpp v233, v233, v233 row_half_mirror row_mask:0xf bank_mask:0x5
	v_add_f32_dpp v233, v235, v235 row_half_mirror row_mask:0xf bank_mask:0xa
	v_add_f32_dpp v248, v232, v232 quad_perm:[2,3,0,1] row_mask:0xf bank_mask:0xf
	s_nop 0
	v_add_f32_dpp v249, v233, v233 quad_perm:[2,3,0,1] row_mask:0xf bank_mask:0xf
	v_cndmask_b32_e64 v232, v248, v249, s[68:69]
	s_nop 1
	v_add_f32_dpp v233, v232, v232 quad_perm:[1,0,3,2] row_mask:0xf bank_mask:0xf
	v_cvt_pk_bf16_f32 v214, v233, v233
	s_mov_b64 exec, s[38:39]
	global_store_short v213, v214, s[10:11] offset:0
	s_mov_b64 exec, -1
	global_store_dwordx4 v132, v[0:3], s[52:53] offset:0
	global_store_dwordx4 v132, v[4:7], s[52:53] offset:256
	global_store_dwordx4 v132, v[8:11], s[52:53] offset:512
	global_store_dwordx4 v132, v[12:15], s[52:53] offset:768
	global_store_dwordx4 v132, v[16:19], s[52:53] offset:1024
	global_store_dwordx4 v132, v[20:23], s[52:53] offset:1280
	global_store_dwordx4 v132, v[24:27], s[52:53] offset:1536
	global_store_dwordx4 v132, v[28:31], s[52:53] offset:1792
	global_store_dwordx4 v132, v[32:35], s[52:53] offset:2048
	global_store_dwordx4 v132, v[36:39], s[52:53] offset:2304
	global_store_dwordx4 v132, v[40:43], s[52:53] offset:2560
	global_store_dwordx4 v132, v[44:47], s[52:53] offset:2816
	global_store_dwordx4 v132, v[48:51], s[52:53] offset:3072
	global_store_dwordx4 v132, v[52:55], s[52:53] offset:3328
	global_store_dwordx4 v132, v[56:59], s[52:53] offset:3584
	global_store_dwordx4 v132, v[60:63], s[52:53] offset:3840
	s_waitcnt vmcnt(20)
	s_add_u32 s20, s47, s33
	s_cmpk_lt_u32 s20, 512
	s_cbranch_scc0 .Lssds_nopf
; __device__ __forceinline__ float bf2f(unsigned h) { return __uint_as_float(h << 16); }
; __device__ __forceinline__ void ssd_sample_items(LAS unsigned char* lds, int it0, int itstride, int nitems, const bf16_t* XBC, const float* DT, const float* a_log,
;                                                  const float* state_in, bf16_t* MIX, float* s_ssm) {
;     ...
;                 const int itn = it + itstride;
;                 if (hh == 0) { const float* sp = state_in + (size_t)(b * NH + h) * HP * NS + 4096;
; #pragma unroll
;                     for (int k = 0; k < 16; ++k) nx[k] = *(const f32x4*)(sp + k * 256 + lane * 4); }
;                 else if (itn < nitems) { const int bn = itn >> 2, gn = itn & 3; const float* sp = state_in + (size_t)(bn * NH + gn * 8 + w) * HP * NS;
; #pragma unroll
;                     for (int k = 0; k < 16; ++k) nx[k] = *(const f32x4*)(sp + k * 256 + lane * 4); }
;             }
;             float yv[4];
; #pragma unroll
;             for (int t = 0; t < 4; ++t) {
;                 const float dt = dtv[t]; const float da = __expf(dt * A);
;                 const f32x4 Bt = (f32x4){bf2f(Bp[t].x & 0xffffu), bf2f(Bp[t].x >> 16), bf2f(Bp[t].y & 0xffffu), bf2f(Bp[t].y >> 16)} * dt;
;                 const f32x4 Ct = (f32x4){bf2f(Cp[t].x & 0xffffu), bf2f(Cp[t].x >> 16), bf2f(Cp[t].y & 0xffffu), bf2f(Cp[t].y >> 16)};
;                 float part[8];
;                 { const bool up8 = (nl & 8) != 0;
; #pragma unroll
;                   for (int i = 0; i < 8; ++i) {
;                     const float x0 = Xs[t * 512 + w * 64 + 32 * hh + 2 * i + half], x1 = Xs[t * 512 + w * 64 + 32 * hh + 2 * (i + 8) + half];
;                     st[i] = st[i] * da + Bt * x0; st[i + 8] = st[i + 8] * da + Bt * x1;
;                     const f32x4 q0 = Ct * st[i], q1 = Ct * st[i + 8];
;                     const float p0 = (q0.x + q0.y) + (q0.z + q0.w), p1 = (q1.x + q1.y) + (q1.z + q1.w);
;                     const float send = up8 ? p0 : p1, keep = up8 ? p1 : p0; part[i] = keep + __shfl_xor(send, 8); } }
;     ...
;                 BFLY(4); BFLY(2); BFLY(1);
;     ...
;                 yv[t] = part[0] + __shfl_xor(part[0], 16);
	s_lshr_b32 s21, s20, 2
	s_and_b32 s22, s20, 3
	s_lshl_b32 s22, s22, 3
	s_add_u32 s22, s22, s46
	s_lshl_b32 s21, s21, 5
	s_add_u32 s21, s21, s22
	s_lshr_b32 s71, s21, 17
	s_lshl_b32 s70, s21, 15
	s_add_u32 s70, s14, s70
	s_addc_u32 s71, s15, s71
	global_load_dwordx4 v[0:3], v132, s[70:71] offset:0
	global_load_dwordx4 v[4:7], v132, s[70:71] offset:256
	global_load_dwordx4 v[8:11], v132, s[70:71] offset:512
	global_load_dwordx4 v[12:15], v132, s[70:71] offset:768
	global_load_dwordx4 v[16:19], v132, s[70:71] offset:1024
	global_load_dwordx4 v[20:23], v132, s[70:71] offset:1280
	global_load_dwordx4 v[24:27], v132, s[70:71] offset:1536
	global_load_dwordx4 v[28:31], v132, s[70:71] offset:1792
	global_load_dwordx4 v[32:35], v132, s[70:71] offset:2048
	global_load_dwordx4 v[36:39], v132, s[70:71] offset:2304
	global_load_dwordx4 v[40:43], v132, s[70:71] offset:2560
	global_load_dwordx4 v[44:47], v132, s[70:71] offset:2816
	global_load_dwordx4 v[48:51], v132, s[70:71] offset:3072
	global_load_dwordx4 v[52:55], v132, s[70:71] offset:3328
	global_load_dwordx4 v[56:59], v132, s[70:71] offset:3584
	global_load_dwordx4 v[60:63], v132, s[70:71] offset:3840
.Lssds_nopf:
	v_lshlrev_b32_e32 v224, 16, v184
	v_and_b32_e32 v225, 0xffff0000, v184
	v_lshlrev_b32_e32 v226, 16, v185
	v_and_b32_e32 v227, 0xffff0000, v185
	v_lshlrev_b32_e32 v228, 16, v186
	v_and_b32_e32 v229, 0xffff0000, v186
	v_lshlrev_b32_e32 v230, 16, v187
	v_and_b32_e32 v231, 0xffff0000, v187
	v_lshlrev_b32_e32 v200, 16, v136
	v_and_b32_e32 v201, 0xffff0000, v136
	v_lshlrev_b32_e32 v202, 16, v137
	v_and_b32_e32 v203, 0xffff0000, v137
	v_lshlrev_b32_e32 v204, 16, v138
	v_and_b32_e32 v205, 0xffff0000, v138
	v_lshlrev_b32_e32 v206, 16, v139
	v_and_b32_e32 v207, 0xffff0000, v139
	v_lshlrev_b32_e32 v216, 16, v152
	v_and_b32_e32 v217, 0xffff0000, v152
	v_lshlrev_b32_e32 v218, 16, v153
	v_and_b32_e32 v219, 0xffff0000, v153
	v_lshlrev_b32_e32 v220, 16, v154
	v_and_b32_e32 v221, 0xffff0000, v154
	v_lshlrev_b32_e32 v222, 16, v155
	v_and_b32_e32 v223, 0xffff0000, v155
	v_pk_mul_f32 v[200:201], v[200:201], v[208:209] op_sel:[0,0] op_sel_hi:[1,0]
	v_pk_mul_f32 v[202:203], v[202:203], v[208:209] op_sel:[0,0] op_sel_hi:[1,0]
	v_pk_mul_f32 v[204:205], v[204:205], v[208:209] op_sel:[0,0] op_sel_hi:[1,0]
	v_pk_mul_f32 v[206:207], v[206:207], v[208:209] op_sel:[0,0] op_sel_hi:[1,0]
	v_pk_mul_f32 v[64:65], v[64:65], v[128:129] op_sel:[0,0] op_sel_hi:[1,0]
	v_pk_mul_f32 v[66:67], v[66:67], v[128:129] op_sel:[0,0] op_sel_hi:[1,0]
	v_pk_fma_f32 v[64:65], v[200:201], v[224:225], v[64:65] op_sel:[0,0,0] op_sel_hi:[1,0,1]
	v_pk_fma_f32 v[66:67], v[202:203], v[224:225], v[66:67] op_sel:[0,0,0] op_sel_hi:[1,0,1]
	v_pk_mul_f32 v[68:69], v[68:69], v[128:129] op_sel:[0,0] op_sel_hi:[1,0]
	v_pk_mul_f32 v[70:71], v[70:71], v[128:129] op_sel:[0,0] op_sel_hi:[1,0]
	v_pk_fma_f32 v[68:69], v[204:205], v[224:225], v[68:69] op_sel:[0,0,0] op_sel_hi:[1,0,1]
	v_pk_fma_f32 v[70:71], v[206:207], v[224:225], v[70:71] op_sel:[0,0,0] op_sel_hi:[1,0,1]
	v_pk_mul_f32 v[240:241], v[216:217], v[64:65]
	v_pk_fma_f32 v[240:241], v[218:219], v[66:67], v[240:241]
	v_pk_fma_f32 v[240:241], v[220:221], v[68:69], v[240:241]
	v_pk_fma_f32 v[240:241], v[222:223], v[70:71], v[240:241]
	v_add_f32_e32 v232, v240, v241
	v_pk_mul_f32 v[72:73], v[72:73], v[128:129] op_sel:[0,0] op_sel_hi:[1,0]
	v_pk_mul_f32 v[74:75], v[74:75], v[128:129] op_sel:[0,0] op_sel_hi:[1,0]
	v_pk_fma_f32 v[72:73], v[200:201], v[224:225], v[72:73] op_sel:[0,1,0] op_sel_hi:[1,1,1]
	v_pk_fma_f32 v[74:75], v[202:203], v[224:225], v[74:75] op_sel:[0,1,0] op_sel_hi:[1,1,1]
	v_pk_mul_f32 v[76:77], v[76:77], v[128:129] op_sel:[0,0] op_sel_hi:[1,0]
	v_pk_mul_f32 v[78:79], v[78:79], v[128:129] op_sel:[0,0] op_sel_hi:[1,0]
	v_pk_fma_f32 v[76:77], v[204:205], v[224:225], v[76:77] op_sel:[0,1,0] op_sel_hi:[1,1,1]
	v_pk_fma_f32 v[78:79], v[206:207], v[224:225], v[78:79] op_sel:[0,1,0] op_sel_hi:[1,1,1]
	v_pk_mul_f32 v[242:243], v[216:217], v[72:73]
	v_pk_fma_f32 v[242:243], v[218:219], v[74:75], v[242:243]
	v_pk_fma_f32 v[242:243], v[220:221], v[76:77], v[242:243]
	v_pk_fma_f32 v[242:243], v[222:223], v[78:79], v[242:243]
	v_add_f32_e32 v233, v242, v243
	v_pk_mul_f32 v[80:81], v[80:81], v[128:129] op_sel:[0,0] op_sel_hi:[1,0]
	v_pk_mul_f32 v[82:83], v[82:83], v[128:129] op_sel:[0,0] op_sel_hi:[1,0]
	v_pk_fma_f32 v[80:81], v[200:201], v[226:227], v[80:81] op_sel:[0,0,0] op_sel_hi:[1,0,1]
	v_pk_fma_f32 v[82:83], v[202:203], v[226:227], v[82:83] op_sel:[0,0,0] op_sel_hi:[1,0,1]
	v_pk_mul_f32 v[84:85], v[84:85], v[128:129] op_sel:[0,0] op_sel_hi:[1,0]
	v_pk_mul_f32 v[86:87], v[86:87], v[128:129] op_sel:[0,0] op_sel_hi:[1,0]
	v_pk_fma_f32 v[84:85], v[204:205], v[226:227], v[84:85] op_sel:[0,0,0] op_sel_hi:[1,0,1]
	v_pk_fma_f32 v[86:87], v[206:207], v[226:227], v[86:87] op_sel:[0,0,0] op_sel_hi:[1,0,1]
	v_pk_mul_f32 v[244:245], v[216:217], v[80:81]
	v_pk_fma_f32 v[244:245], v[218:219], v[82:83], v[244:245]
	v_pk_fma_f32 v[244:245], v[220:221], v[84:85], v[244:245]
	v_pk_fma_f32 v[244:245], v[222:223], v[86:87], v[244:245]
	v_add_f32_e32 v234, v244, v245
	v_pk_mul_f32 v[88:89], v[88:89], v[128:129] op_sel:[0,0] op_sel_hi:[1,0]
	v_pk_mul_f32 v[90:91], v[90:91], v[128:129] op_sel:[0,0] op_sel_hi:[1,0]
	v_pk_fma_f32 v[88:89], v[200:201], v[226:227], v[88:89] op_sel:[0,1,0] op_sel_hi:[1,1,1]
	v_pk_fma_f32 v[90:91], v[202:203], v[226:227], v[90:91] op_sel:[0,1,0] op_sel_hi:[1,1,1]
	v_pk_mul_f32 v[92:93], v[92:93], v[128:129] op_sel:[0,0] op_sel_hi:[1,0]
	v_pk_mul_f32 v[94:95], v[94:95], v[128:129] op_sel:[0,0] op_sel_hi:[1,0]
	v_pk_fma_f32 v[92:93], v[204:205], v[226:227], v[92:93] op_sel:[0,1,0] op_sel_hi:[1,1,1]
; __device__ __forceinline__ float bf2f(unsigned h) { return __uint_as_float(h << 16); }
; __device__ __forceinline__ unsigned f2bf(float f) { unsigned u = __float_as_uint(f); return (u + 0x7fffu + ((u >> 16) & 1u)) >> 16; }
; #define BFLY(o) do { const bool up = (nl & (o)) != 0; _Pragma("unroll") for (int i = 0; i < (o); ++i) { \
;                     const float send = up ? part[i] : part[i + (o)]; const float keep = up ? part[i + (o)] : part[i]; part[i] = keep + __shfl_xor(send, (o)); } } while (0)
; __device__ __forceinline__ void ssd_sample_items(LAS unsigned char* lds, int it0, int itstride, int nitems, const bf16_t* XBC, const float* DT, const float* a_log,
;                                                  const float* state_in, bf16_t* MIX, float* s_ssm) {
;     ...
;             for (int t = 0; t < 4; ++t) {
;                 const float dt = dtv[t]; const float da = __expf(dt * A);
;                 const f32x4 Bt = (f32x4){bf2f(Bp[t].x & 0xffffu), bf2f(Bp[t].x >> 16), bf2f(Bp[t].y & 0xffffu), bf2f(Bp[t].y >> 16)} * dt;
;                 const f32x4 Ct = (f32x4){bf2f(Cp[t].x & 0xffffu), bf2f(Cp[t].x >> 16), bf2f(Cp[t].y & 0xffffu), bf2f(Cp[t].y >> 16)};
;                 float part[8];
;                 { const bool up8 = (nl & 8) != 0;
; #pragma unroll
;                   for (int i = 0; i < 8; ++i) {
;                     const float x0 = Xs[t * 512 + w * 64 + 32 * hh + 2 * i + half], x1 = Xs[t * 512 + w * 64 + 32 * hh + 2 * (i + 8) + half];
;                     st[i] = st[i] * da + Bt * x0; st[i + 8] = st[i + 8] * da + Bt * x1;
;                     const f32x4 q0 = Ct * st[i], q1 = Ct * st[i + 8];
;                     const float p0 = (q0.x + q0.y) + (q0.z + q0.w), p1 = (q1.x + q1.y) + (q1.z + q1.w);
;                     const float send = up8 ? p0 : p1, keep = up8 ? p1 : p0; part[i] = keep + __shfl_xor(send, 8); } }
;     ...
;                 BFLY(4); BFLY(2); BFLY(1);
;     ...
;                 yv[t] = part[0] + __shfl_xor(part[0], 16);
;             }
;             const int pout = 32 * hh + 2 * (nl & 15) + half;
;             if ((nl & 16) == 0) {
; #pragma unroll
;                 for (int t = 0; t < 4; ++t) MIX[(size_t)(MP + 4 * b + t) * DMIX + h * 64 + pout] = (bf16_t)f2bf(yv[t]);
;             }
	v_pk_fma_f32 v[94:95], v[206:207], v[226:227], v[94:95] op_sel:[0,1,0] op_sel_hi:[1,1,1]
	v_pk_mul_f32 v[246:247], v[216:217], v[88:89]
	v_pk_fma_f32 v[246:247], v[218:219], v[90:91], v[246:247]
	v_pk_fma_f32 v[246:247], v[220:221], v[92:93], v[246:247]
	v_pk_fma_f32 v[246:247], v[222:223], v[94:95], v[246:247]
	v_add_f32_e32 v235, v246, v247
	v_pk_mul_f32 v[96:97], v[96:97], v[128:129] op_sel:[0,0] op_sel_hi:[1,0]
	v_pk_mul_f32 v[98:99], v[98:99], v[128:129] op_sel:[0,0] op_sel_hi:[1,0]
	v_pk_fma_f32 v[96:97], v[200:201], v[228:229], v[96:97] op_sel:[0,0,0] op_sel_hi:[1,0,1]
	v_pk_fma_f32 v[98:99], v[202:203], v[228:229], v[98:99] op_sel:[0,0,0] op_sel_hi:[1,0,1]
	v_pk_mul_f32 v[100:101], v[100:101], v[128:129] op_sel:[0,0] op_sel_hi:[1,0]
	v_pk_mul_f32 v[102:103], v[102:103], v[128:129] op_sel:[0,0] op_sel_hi:[1,0]
	v_pk_fma_f32 v[100:101], v[204:205], v[228:229], v[100:101] op_sel:[0,0,0] op_sel_hi:[1,0,1]
	v_pk_fma_f32 v[102:103], v[206:207], v[228:229], v[102:103] op_sel:[0,0,0] op_sel_hi:[1,0,1]
	v_pk_mul_f32 v[240:241], v[216:217], v[96:97]
	v_pk_fma_f32 v[240:241], v[218:219], v[98:99], v[240:241]
	v_pk_fma_f32 v[240:241], v[220:221], v[100:101], v[240:241]
	v_pk_fma_f32 v[240:241], v[222:223], v[102:103], v[240:241]
	v_add_f32_e32 v236, v240, v241
	v_pk_mul_f32 v[104:105], v[104:105], v[128:129] op_sel:[0,0] op_sel_hi:[1,0]
	v_pk_mul_f32 v[106:107], v[106:107], v[128:129] op_sel:[0,0] op_sel_hi:[1,0]
	v_pk_fma_f32 v[104:105], v[200:201], v[228:229], v[104:105] op_sel:[0,1,0] op_sel_hi:[1,1,1]
	v_pk_fma_f32 v[106:107], v[202:203], v[228:229], v[106:107] op_sel:[0,1,0] op_sel_hi:[1,1,1]
	v_pk_mul_f32 v[108:109], v[108:109], v[128:129] op_sel:[0,0] op_sel_hi:[1,0]
	v_pk_mul_f32 v[110:111], v[110:111], v[128:129] op_sel:[0,0] op_sel_hi:[1,0]
	v_pk_fma_f32 v[108:109], v[204:205], v[228:229], v[108:109] op_sel:[0,1,0] op_sel_hi:[1,1,1]
	v_pk_fma_f32 v[110:111], v[206:207], v[228:229], v[110:111] op_sel:[0,1,0] op_sel_hi:[1,1,1]
	v_pk_mul_f32 v[242:243], v[216:217], v[104:105]
	v_pk_fma_f32 v[242:243], v[218:219], v[106:107], v[242:243]
	v_pk_fma_f32 v[242:243], v[220:221], v[108:109], v[242:243]
	v_pk_fma_f32 v[242:243], v[222:223], v[110:111], v[242:243]
	v_add_f32_e32 v237, v242, v243
	v_pk_mul_f32 v[112:113], v[112:113], v[128:129] op_sel:[0,0] op_sel_hi:[1,0]
	v_pk_mul_f32 v[114:115], v[114:115], v[128:129] op_sel:[0,0] op_sel_hi:[1,0]
	v_pk_fma_f32 v[112:113], v[200:201], v[230:231], v[112:113] op_sel:[0,0,0] op_sel_hi:[1,0,1]
	v_pk_fma_f32 v[114:115], v[202:203], v[230:231], v[114:115] op_sel:[0,0,0] op_sel_hi:[1,0,1]
	v_pk_mul_f32 v[116:117], v[116:117], v[128:129] op_sel:[0,0] op_sel_hi:[1,0]
	v_pk_mul_f32 v[118:119], v[118:119], v[128:129] op_sel:[0,0] op_sel_hi:[1,0]
	v_pk_fma_f32 v[116:117], v[204:205], v[230:231], v[116:117] op_sel:[0,0,0] op_sel_hi:[1,0,1]
	v_pk_fma_f32 v[118:119], v[206:207], v[230:231], v[118:119] op_sel:[0,0,0] op_sel_hi:[1,0,1]
	v_pk_mul_f32 v[244:245], v[216:217], v[112:113]
	v_pk_fma_f32 v[244:245], v[218:219], v[114:115], v[244:245]
	v_pk_fma_f32 v[244:245], v[220:221], v[116:117], v[244:245]
	v_pk_fma_f32 v[244:245], v[222:223], v[118:119], v[244:245]
	v_add_f32_e32 v238, v244, v245
	v_pk_mul_f32 v[120:121], v[120:121], v[128:129] op_sel:[0,0] op_sel_hi:[1,0]
	v_pk_mul_f32 v[122:123], v[122:123], v[128:129] op_sel:[0,0] op_sel_hi:[1,0]
	v_pk_fma_f32 v[120:121], v[200:201], v[230:231], v[120:121] op_sel:[0,1,0] op_sel_hi:[1,1,1]
	v_pk_fma_f32 v[122:123], v[202:203], v[230:231], v[122:123] op_sel:[0,1,0] op_sel_hi:[1,1,1]
	v_pk_mul_f32 v[124:125], v[124:125], v[128:129] op_sel:[0,0] op_sel_hi:[1,0]
	v_pk_mul_f32 v[126:127], v[126:127], v[128:129] op_sel:[0,0] op_sel_hi:[1,0]
	v_pk_fma_f32 v[124:125], v[204:205], v[230:231], v[124:125] op_sel:[0,1,0] op_sel_hi:[1,1,1]
	v_pk_fma_f32 v[126:127], v[206:207], v[230:231], v[126:127] op_sel:[0,1,0] op_sel_hi:[1,1,1]
	v_pk_mul_f32 v[246:247], v[216:217], v[120:121]
	v_pk_fma_f32 v[246:247], v[218:219], v[122:123], v[246:247]
	v_pk_fma_f32 v[246:247], v[220:221], v[124:125], v[246:247]
	v_pk_fma_f32 v[246:247], v[222:223], v[126:127], v[246:247]
	v_add_f32_e32 v239, v246, v247
	v_add_f32_dpp v232, v232, v232 row_mirror row_mask:0xf bank_mask:0x3
	v_add_f32_dpp v232, v236, v236 row_mirror row_mask:0xf bank_mask:0xc
	v_add_f32_dpp v233, v233, v233 row_mirror row_mask:0xf bank_mask:0x3
	v_add_f32_dpp v233, v237, v237 row_mirror row_mask:0xf bank_mask:0xc
	v_add_f32_dpp v234, v234, v234 row_mirror row_mask:0xf bank_mask:0x3
	v_add_f32_dpp v234, v238, v238 row_mirror row_mask:0xf bank_mask:0xc
	v_add_f32_dpp v235, v235, v235 row_mirror row_mask:0xf bank_mask:0x3
	v_add_f32_dpp v235, v239, v239 row_mirror row_mask:0xf bank_mask:0xc
	v_add_f32_dpp v232, v232, v232 row_half_mirror row_mask:0xf bank_mask:0x5
	v_add_f32_dpp v232, v234, v234 row_half_mirror row_mask:0xf bank_mask:0xa
	v_add_f32_dpp v233, v233, v233 row_half_mirror row_mask:0xf bank_mask:0x5
	v_add_f32_dpp v233, v235, v235 row_half_mirror row_mask:0xf bank_mask:0xa
	v_add_f32_dpp v248, v232, v232 quad_perm:[2,3,0,1] row_mask:0xf bank_mask:0xf
	s_nop 0
	v_add_f32_dpp v249, v233, v233 quad_perm:[2,3,0,1] row_mask:0xf bank_mask:0xf
	v_cndmask_b32_e64 v232, v248, v249, s[68:69]
	s_nop 1
	v_add_f32_dpp v233, v232, v232 quad_perm:[1,0,3,2] row_mask:0xf bank_mask:0xf
	v_cvt_pk_bf16_f32 v214, v233, v233
	s_mov_b64 exec, s[38:39]
	global_store_short v213, v214, s[4:5] offset:64
	s_mov_b64 exec, -1
	v_lshlrev_b32_e32 v224, 16, v188
	v_and_b32_e32 v225, 0xffff0000, v188
	v_lshlrev_b32_e32 v226, 16, v189
	v_and_b32_e32 v227, 0xffff0000, v189
	v_lshlrev_b32_e32 v228, 16, v190
	v_and_b32_e32 v229, 0xffff0000, v190
; __device__ __forceinline__ float bf2f(unsigned h) { return __uint_as_float(h << 16); }
; __device__ __forceinline__ void ssd_sample_items(LAS unsigned char* lds, int it0, int itstride, int nitems, const bf16_t* XBC, const float* DT, const float* a_log,
;                                                  const float* state_in, bf16_t* MIX, float* s_ssm) {
;     ...
;             for (int t = 0; t < 4; ++t) {
;                 const float dt = dtv[t]; const float da = __expf(dt * A);
;                 const f32x4 Bt = (f32x4){bf2f(Bp[t].x & 0xffffu), bf2f(Bp[t].x >> 16), bf2f(Bp[t].y & 0xffffu), bf2f(Bp[t].y >> 16)} * dt;
;                 const f32x4 Ct = (f32x4){bf2f(Cp[t].x & 0xffffu), bf2f(Cp[t].x >> 16), bf2f(Cp[t].y & 0xffffu), bf2f(Cp[t].y >> 16)};
;                 float part[8];
;                 { const bool up8 = (nl & 8) != 0;
; #pragma unroll
;                   for (int i = 0; i < 8; ++i) {
;                     const float x0 = Xs[t * 512 + w * 64 + 32 * hh + 2 * i + half], x1 = Xs[t * 512 + w * 64 + 32 * hh + 2 * (i + 8) + half];
;                     st[i] = st[i] * da + Bt * x0; st[i + 8] = st[i + 8] * da + Bt * x1;
;                     const f32x4 q0 = Ct * st[i], q1 = Ct * st[i + 8];
;                     const float p0 = (q0.x + q0.y) + (q0.z + q0.w), p1 = (q1.x + q1.y) + (q1.z + q1.w);
;                     const float send = up8 ? p0 : p1, keep = up8 ? p1 : p0; part[i] = keep + __shfl_xor(send, 8); } }
	v_lshlrev_b32_e32 v230, 16, v191
	v_and_b32_e32 v231, 0xffff0000, v191
	v_lshlrev_b32_e32 v200, 16, v140
	v_and_b32_e32 v201, 0xffff0000, v140
	v_lshlrev_b32_e32 v202, 16, v141
	v_and_b32_e32 v203, 0xffff0000, v141
	v_lshlrev_b32_e32 v204, 16, v142
	v_and_b32_e32 v205, 0xffff0000, v142
	v_lshlrev_b32_e32 v206, 16, v143
	v_and_b32_e32 v207, 0xffff0000, v143
	v_lshlrev_b32_e32 v216, 16, v156
	v_and_b32_e32 v217, 0xffff0000, v156
	v_lshlrev_b32_e32 v218, 16, v157
	v_and_b32_e32 v219, 0xffff0000, v157
	v_lshlrev_b32_e32 v220, 16, v158
	v_and_b32_e32 v221, 0xffff0000, v158
	v_lshlrev_b32_e32 v222, 16, v159
	v_and_b32_e32 v223, 0xffff0000, v159
	v_pk_mul_f32 v[200:201], v[200:201], v[208:209] op_sel:[0,1] op_sel_hi:[1,1]
	v_pk_mul_f32 v[202:203], v[202:203], v[208:209] op_sel:[0,1] op_sel_hi:[1,1]
	v_pk_mul_f32 v[204:205], v[204:205], v[208:209] op_sel:[0,1] op_sel_hi:[1,1]
	v_pk_mul_f32 v[206:207], v[206:207], v[208:209] op_sel:[0,1] op_sel_hi:[1,1]
	v_pk_mul_f32 v[64:65], v[64:65], v[128:129] op_sel:[0,1] op_sel_hi:[1,1]
	v_pk_mul_f32 v[66:67], v[66:67], v[128:129] op_sel:[0,1] op_sel_hi:[1,1]
	v_pk_fma_f32 v[64:65], v[200:201], v[224:225], v[64:65] op_sel:[0,0,0] op_sel_hi:[1,0,1]
	v_pk_fma_f32 v[66:67], v[202:203], v[224:225], v[66:67] op_sel:[0,0,0] op_sel_hi:[1,0,1]
	v_pk_mul_f32 v[68:69], v[68:69], v[128:129] op_sel:[0,1] op_sel_hi:[1,1]
	v_pk_mul_f32 v[70:71], v[70:71], v[128:129] op_sel:[0,1] op_sel_hi:[1,1]
	v_pk_fma_f32 v[68:69], v[204:205], v[224:225], v[68:69] op_sel:[0,0,0] op_sel_hi:[1,0,1]
	v_pk_fma_f32 v[70:71], v[206:207], v[224:225], v[70:71] op_sel:[0,0,0] op_sel_hi:[1,0,1]
	v_pk_mul_f32 v[240:241], v[216:217], v[64:65]
	v_pk_fma_f32 v[240:241], v[218:219], v[66:67], v[240:241]
	v_pk_fma_f32 v[240:241], v[220:221], v[68:69], v[240:241]
	v_pk_fma_f32 v[240:241], v[222:223], v[70:71], v[240:241]
	v_add_f32_e32 v232, v240, v241
	v_pk_mul_f32 v[72:73], v[72:73], v[128:129] op_sel:[0,1] op_sel_hi:[1,1]
	v_pk_mul_f32 v[74:75], v[74:75], v[128:129] op_sel:[0,1] op_sel_hi:[1,1]
	v_pk_fma_f32 v[72:73], v[200:201], v[224:225], v[72:73] op_sel:[0,1,0] op_sel_hi:[1,1,1]
	v_pk_fma_f32 v[74:75], v[202:203], v[224:225], v[74:75] op_sel:[0,1,0] op_sel_hi:[1,1,1]
	v_pk_mul_f32 v[76:77], v[76:77], v[128:129] op_sel:[0,1] op_sel_hi:[1,1]
	v_pk_mul_f32 v[78:79], v[78:79], v[128:129] op_sel:[0,1] op_sel_hi:[1,1]
	v_pk_fma_f32 v[76:77], v[204:205], v[224:225], v[76:77] op_sel:[0,1,0] op_sel_hi:[1,1,1]
	v_pk_fma_f32 v[78:79], v[206:207], v[224:225], v[78:79] op_sel:[0,1,0] op_sel_hi:[1,1,1]
	v_pk_mul_f32 v[242:243], v[216:217], v[72:73]
	v_pk_fma_f32 v[242:243], v[218:219], v[74:75], v[242:243]
	v_pk_fma_f32 v[242:243], v[220:221], v[76:77], v[242:243]
	v_pk_fma_f32 v[242:243], v[222:223], v[78:79], v[242:243]
	v_add_f32_e32 v233, v242, v243
	v_pk_mul_f32 v[80:81], v[80:81], v[128:129] op_sel:[0,1] op_sel_hi:[1,1]
	v_pk_mul_f32 v[82:83], v[82:83], v[128:129] op_sel:[0,1] op_sel_hi:[1,1]
	v_pk_fma_f32 v[80:81], v[200:201], v[226:227], v[80:81] op_sel:[0,0,0] op_sel_hi:[1,0,1]
	v_pk_fma_f32 v[82:83], v[202:203], v[226:227], v[82:83] op_sel:[0,0,0] op_sel_hi:[1,0,1]
	v_pk_mul_f32 v[84:85], v[84:85], v[128:129] op_sel:[0,1] op_sel_hi:[1,1]
	v_pk_mul_f32 v[86:87], v[86:87], v[128:129] op_sel:[0,1] op_sel_hi:[1,1]
	v_pk_fma_f32 v[84:85], v[204:205], v[226:227], v[84:85] op_sel:[0,0,0] op_sel_hi:[1,0,1]
	v_pk_fma_f32 v[86:87], v[206:207], v[226:227], v[86:87] op_sel:[0,0,0] op_sel_hi:[1,0,1]
	v_pk_mul_f32 v[244:245], v[216:217], v[80:81]
	v_pk_fma_f32 v[244:245], v[218:219], v[82:83], v[244:245]
	v_pk_fma_f32 v[244:245], v[220:221], v[84:85], v[244:245]
	v_pk_fma_f32 v[244:245], v[222:223], v[86:87], v[244:245]
	v_add_f32_e32 v234, v244, v245
	v_pk_mul_f32 v[88:89], v[88:89], v[128:129] op_sel:[0,1] op_sel_hi:[1,1]
	v_pk_mul_f32 v[90:91], v[90:91], v[128:129] op_sel:[0,1] op_sel_hi:[1,1]
	v_pk_fma_f32 v[88:89], v[200:201], v[226:227], v[88:89] op_sel:[0,1,0] op_sel_hi:[1,1,1]
	v_pk_fma_f32 v[90:91], v[202:203], v[226:227], v[90:91] op_sel:[0,1,0] op_sel_hi:[1,1,1]
	v_pk_mul_f32 v[92:93], v[92:93], v[128:129] op_sel:[0,1] op_sel_hi:[1,1]
	v_pk_mul_f32 v[94:95], v[94:95], v[128:129] op_sel:[0,1] op_sel_hi:[1,1]
	v_pk_fma_f32 v[92:93], v[204:205], v[226:227], v[92:93] op_sel:[0,1,0] op_sel_hi:[1,1,1]
	v_pk_fma_f32 v[94:95], v[206:207], v[226:227], v[94:95] op_sel:[0,1,0] op_sel_hi:[1,1,1]
	v_pk_mul_f32 v[246:247], v[216:217], v[88:89]
	v_pk_fma_f32 v[246:247], v[218:219], v[90:91], v[246:247]
	v_pk_fma_f32 v[246:247], v[220:221], v[92:93], v[246:247]
	v_pk_fma_f32 v[246:247], v[222:223], v[94:95], v[246:247]
	v_add_f32_e32 v235, v246, v247
	v_pk_mul_f32 v[96:97], v[96:97], v[128:129] op_sel:[0,1] op_sel_hi:[1,1]
	v_pk_mul_f32 v[98:99], v[98:99], v[128:129] op_sel:[0,1] op_sel_hi:[1,1]
	v_pk_fma_f32 v[96:97], v[200:201], v[228:229], v[96:97] op_sel:[0,0,0] op_sel_hi:[1,0,1]
	v_pk_fma_f32 v[98:99], v[202:203], v[228:229], v[98:99] op_sel:[0,0,0] op_sel_hi:[1,0,1]
	v_pk_mul_f32 v[100:101], v[100:101], v[128:129] op_sel:[0,1] op_sel_hi:[1,1]
	v_pk_mul_f32 v[102:103], v[102:103], v[128:129] op_sel:[0,1] op_sel_hi:[1,1]
	v_pk_fma_f32 v[100:101], v[204:205], v[228:229], v[100:101] op_sel:[0,0,0] op_sel_hi:[1,0,1]
	v_pk_fma_f32 v[102:103], v[206:207], v[228:229], v[102:103] op_sel:[0,0,0] op_sel_hi:[1,0,1]
	v_pk_mul_f32 v[240:241], v[216:217], v[96:97]
	v_pk_fma_f32 v[240:241], v[218:219], v[98:99], v[240:241]
	v_pk_fma_f32 v[240:241], v[220:221], v[100:101], v[240:241]
	v_pk_fma_f32 v[240:241], v[222:223], v[102:103], v[240:241]
	v_add_f32_e32 v236, v240, v241
	v_pk_mul_f32 v[104:105], v[104:105], v[128:129] op_sel:[0,1] op_sel_hi:[1,1]
; __device__ __forceinline__ float bf2f(unsigned h) { return __uint_as_float(h << 16); }
; __device__ __forceinline__ unsigned f2bf(float f) { unsigned u = __float_as_uint(f); return (u + 0x7fffu + ((u >> 16) & 1u)) >> 16; }
; #define BFLY(o) do { const bool up = (nl & (o)) != 0; _Pragma("unroll") for (int i = 0; i < (o); ++i) { \
;                     const float send = up ? part[i] : part[i + (o)]; const float keep = up ? part[i + (o)] : part[i]; part[i] = keep + __shfl_xor(send, (o)); } } while (0)
; __device__ __forceinline__ void ssd_sample_items(LAS unsigned char* lds, int it0, int itstride, int nitems, const bf16_t* XBC, const float* DT, const float* a_log,
;                                                  const float* state_in, bf16_t* MIX, float* s_ssm) {
;     ...
;             for (int t = 0; t < 4; ++t) {
;                 const float dt = dtv[t]; const float da = __expf(dt * A);
;                 const f32x4 Bt = (f32x4){bf2f(Bp[t].x & 0xffffu), bf2f(Bp[t].x >> 16), bf2f(Bp[t].y & 0xffffu), bf2f(Bp[t].y >> 16)} * dt;
;                 const f32x4 Ct = (f32x4){bf2f(Cp[t].x & 0xffffu), bf2f(Cp[t].x >> 16), bf2f(Cp[t].y & 0xffffu), bf2f(Cp[t].y >> 16)};
;                 float part[8];
;                 { const bool up8 = (nl & 8) != 0;
; #pragma unroll
;                   for (int i = 0; i < 8; ++i) {
;                     const float x0 = Xs[t * 512 + w * 64 + 32 * hh + 2 * i + half], x1 = Xs[t * 512 + w * 64 + 32 * hh + 2 * (i + 8) + half];
;                     st[i] = st[i] * da + Bt * x0; st[i + 8] = st[i + 8] * da + Bt * x1;
;                     const f32x4 q0 = Ct * st[i], q1 = Ct * st[i + 8];
;                     const float p0 = (q0.x + q0.y) + (q0.z + q0.w), p1 = (q1.x + q1.y) + (q1.z + q1.w);
;                     const float send = up8 ? p0 : p1, keep = up8 ? p1 : p0; part[i] = keep + __shfl_xor(send, 8); } }
;     ...
;                 BFLY(4); BFLY(2); BFLY(1);
;     ...
;                 yv[t] = part[0] + __shfl_xor(part[0], 16);
;             }
;             const int pout = 32 * hh + 2 * (nl & 15) + half;
;             if ((nl & 16) == 0) {
; #pragma unroll
;                 for (int t = 0; t < 4; ++t) MIX[(size_t)(MP + 4 * b + t) * DMIX + h * 64 + pout] = (bf16_t)f2bf(yv[t]);
;             }
	v_pk_mul_f32 v[106:107], v[106:107], v[128:129] op_sel:[0,1] op_sel_hi:[1,1]
	v_pk_fma_f32 v[104:105], v[200:201], v[228:229], v[104:105] op_sel:[0,1,0] op_sel_hi:[1,1,1]
	v_pk_fma_f32 v[106:107], v[202:203], v[228:229], v[106:107] op_sel:[0,1,0] op_sel_hi:[1,1,1]
	v_pk_mul_f32 v[108:109], v[108:109], v[128:129] op_sel:[0,1] op_sel_hi:[1,1]
	v_pk_mul_f32 v[110:111], v[110:111], v[128:129] op_sel:[0,1] op_sel_hi:[1,1]
	v_pk_fma_f32 v[108:109], v[204:205], v[228:229], v[108:109] op_sel:[0,1,0] op_sel_hi:[1,1,1]
	v_pk_fma_f32 v[110:111], v[206:207], v[228:229], v[110:111] op_sel:[0,1,0] op_sel_hi:[1,1,1]
	v_pk_mul_f32 v[242:243], v[216:217], v[104:105]
	v_pk_fma_f32 v[242:243], v[218:219], v[106:107], v[242:243]
	v_pk_fma_f32 v[242:243], v[220:221], v[108:109], v[242:243]
	v_pk_fma_f32 v[242:243], v[222:223], v[110:111], v[242:243]
	v_add_f32_e32 v237, v242, v243
	v_pk_mul_f32 v[112:113], v[112:113], v[128:129] op_sel:[0,1] op_sel_hi:[1,1]
	v_pk_mul_f32 v[114:115], v[114:115], v[128:129] op_sel:[0,1] op_sel_hi:[1,1]
	v_pk_fma_f32 v[112:113], v[200:201], v[230:231], v[112:113] op_sel:[0,0,0] op_sel_hi:[1,0,1]
	v_pk_fma_f32 v[114:115], v[202:203], v[230:231], v[114:115] op_sel:[0,0,0] op_sel_hi:[1,0,1]
	v_pk_mul_f32 v[116:117], v[116:117], v[128:129] op_sel:[0,1] op_sel_hi:[1,1]
	v_pk_mul_f32 v[118:119], v[118:119], v[128:129] op_sel:[0,1] op_sel_hi:[1,1]
	v_pk_fma_f32 v[116:117], v[204:205], v[230:231], v[116:117] op_sel:[0,0,0] op_sel_hi:[1,0,1]
	v_pk_fma_f32 v[118:119], v[206:207], v[230:231], v[118:119] op_sel:[0,0,0] op_sel_hi:[1,0,1]
	v_pk_mul_f32 v[244:245], v[216:217], v[112:113]
	v_pk_fma_f32 v[244:245], v[218:219], v[114:115], v[244:245]
	v_pk_fma_f32 v[244:245], v[220:221], v[116:117], v[244:245]
	v_pk_fma_f32 v[244:245], v[222:223], v[118:119], v[244:245]
	v_add_f32_e32 v238, v244, v245
	v_pk_mul_f32 v[120:121], v[120:121], v[128:129] op_sel:[0,1] op_sel_hi:[1,1]
	v_pk_mul_f32 v[122:123], v[122:123], v[128:129] op_sel:[0,1] op_sel_hi:[1,1]
	v_pk_fma_f32 v[120:121], v[200:201], v[230:231], v[120:121] op_sel:[0,1,0] op_sel_hi:[1,1,1]
	v_pk_fma_f32 v[122:123], v[202:203], v[230:231], v[122:123] op_sel:[0,1,0] op_sel_hi:[1,1,1]
	v_pk_mul_f32 v[124:125], v[124:125], v[128:129] op_sel:[0,1] op_sel_hi:[1,1]
	v_pk_mul_f32 v[126:127], v[126:127], v[128:129] op_sel:[0,1] op_sel_hi:[1,1]
	v_pk_fma_f32 v[124:125], v[204:205], v[230:231], v[124:125] op_sel:[0,1,0] op_sel_hi:[1,1,1]
	v_pk_fma_f32 v[126:127], v[206:207], v[230:231], v[126:127] op_sel:[0,1,0] op_sel_hi:[1,1,1]
	v_pk_mul_f32 v[246:247], v[216:217], v[120:121]
	v_pk_fma_f32 v[246:247], v[218:219], v[122:123], v[246:247]
	v_pk_fma_f32 v[246:247], v[220:221], v[124:125], v[246:247]
	v_pk_fma_f32 v[246:247], v[222:223], v[126:127], v[246:247]
	v_add_f32_e32 v239, v246, v247
	v_add_f32_dpp v232, v232, v232 row_mirror row_mask:0xf bank_mask:0x3
	v_add_f32_dpp v232, v236, v236 row_mirror row_mask:0xf bank_mask:0xc
	v_add_f32_dpp v233, v233, v233 row_mirror row_mask:0xf bank_mask:0x3
	v_add_f32_dpp v233, v237, v237 row_mirror row_mask:0xf bank_mask:0xc
	v_add_f32_dpp v234, v234, v234 row_mirror row_mask:0xf bank_mask:0x3
	v_add_f32_dpp v234, v238, v238 row_mirror row_mask:0xf bank_mask:0xc
	v_add_f32_dpp v235, v235, v235 row_mirror row_mask:0xf bank_mask:0x3
	v_add_f32_dpp v235, v239, v239 row_mirror row_mask:0xf bank_mask:0xc
	v_add_f32_dpp v232, v232, v232 row_half_mirror row_mask:0xf bank_mask:0x5
	v_add_f32_dpp v232, v234, v234 row_half_mirror row_mask:0xf bank_mask:0xa
	v_add_f32_dpp v233, v233, v233 row_half_mirror row_mask:0xf bank_mask:0x5
	v_add_f32_dpp v233, v235, v235 row_half_mirror row_mask:0xf bank_mask:0xa
	v_add_f32_dpp v248, v232, v232 quad_perm:[2,3,0,1] row_mask:0xf bank_mask:0xf
	s_nop 0
	v_add_f32_dpp v249, v233, v233 quad_perm:[2,3,0,1] row_mask:0xf bank_mask:0xf
	v_cndmask_b32_e64 v232, v248, v249, s[68:69]
	s_nop 1
	v_add_f32_dpp v233, v232, v232 quad_perm:[1,0,3,2] row_mask:0xf bank_mask:0xf
	v_cvt_pk_bf16_f32 v214, v233, v233
	s_mov_b64 exec, s[38:39]
	global_store_short v213, v214, s[6:7] offset:64
	s_mov_b64 exec, -1
	v_lshlrev_b32_e32 v224, 16, v192
	v_and_b32_e32 v225, 0xffff0000, v192
	v_lshlrev_b32_e32 v226, 16, v193
	v_and_b32_e32 v227, 0xffff0000, v193
	v_lshlrev_b32_e32 v228, 16, v194
	v_and_b32_e32 v229, 0xffff0000, v194
	v_lshlrev_b32_e32 v230, 16, v195
	v_and_b32_e32 v231, 0xffff0000, v195
	v_lshlrev_b32_e32 v200, 16, v144
	v_and_b32_e32 v201, 0xffff0000, v144
	v_lshlrev_b32_e32 v202, 16, v145
	v_and_b32_e32 v203, 0xffff0000, v145
	v_lshlrev_b32_e32 v204, 16, v146
	v_and_b32_e32 v205, 0xffff0000, v146
	v_lshlrev_b32_e32 v206, 16, v147
	v_and_b32_e32 v207, 0xffff0000, v147
	v_lshlrev_b32_e32 v216, 16, v160
	v_and_b32_e32 v217, 0xffff0000, v160
	v_lshlrev_b32_e32 v218, 16, v161
	v_and_b32_e32 v219, 0xffff0000, v161
	v_lshlrev_b32_e32 v220, 16, v162
	v_and_b32_e32 v221, 0xffff0000, v162
	v_lshlrev_b32_e32 v222, 16, v163
	v_and_b32_e32 v223, 0xffff0000, v163
	v_pk_mul_f32 v[200:201], v[200:201], v[210:211] op_sel:[0,0] op_sel_hi:[1,0]
	v_pk_mul_f32 v[202:203], v[202:203], v[210:211] op_sel:[0,0] op_sel_hi:[1,0]
	v_pk_mul_f32 v[204:205], v[204:205], v[210:211] op_sel:[0,0] op_sel_hi:[1,0]
	v_pk_mul_f32 v[206:207], v[206:207], v[210:211] op_sel:[0,0] op_sel_hi:[1,0]
	v_pk_mul_f32 v[64:65], v[64:65], v[130:131] op_sel:[0,0] op_sel_hi:[1,0]
	v_pk_mul_f32 v[66:67], v[66:67], v[130:131] op_sel:[0,0] op_sel_hi:[1,0]
	v_pk_fma_f32 v[64:65], v[200:201], v[224:225], v[64:65] op_sel:[0,0,0] op_sel_hi:[1,0,1]
	v_pk_fma_f32 v[66:67], v[202:203], v[224:225], v[66:67] op_sel:[0,0,0] op_sel_hi:[1,0,1]
	v_pk_mul_f32 v[68:69], v[68:69], v[130:131] op_sel:[0,0] op_sel_hi:[1,0]
; __device__ __forceinline__ float bf2f(unsigned h) { return __uint_as_float(h << 16); }
; __device__ __forceinline__ void ssd_sample_items(LAS unsigned char* lds, int it0, int itstride, int nitems, const bf16_t* XBC, const float* DT, const float* a_log,
;                                                  const float* state_in, bf16_t* MIX, float* s_ssm) {
;     ...
;             for (int t = 0; t < 4; ++t) {
;                 const float dt = dtv[t]; const float da = __expf(dt * A);
;                 const f32x4 Bt = (f32x4){bf2f(Bp[t].x & 0xffffu), bf2f(Bp[t].x >> 16), bf2f(Bp[t].y & 0xffffu), bf2f(Bp[t].y >> 16)} * dt;
;                 const f32x4 Ct = (f32x4){bf2f(Cp[t].x & 0xffffu), bf2f(Cp[t].x >> 16), bf2f(Cp[t].y & 0xffffu), bf2f(Cp[t].y >> 16)};
;                 float part[8];
;                 { const bool up8 = (nl & 8) != 0;
; #pragma unroll
;                   for (int i = 0; i < 8; ++i) {
;                     const float x0 = Xs[t * 512 + w * 64 + 32 * hh + 2 * i + half], x1 = Xs[t * 512 + w * 64 + 32 * hh + 2 * (i + 8) + half];
;                     st[i] = st[i] * da + Bt * x0; st[i + 8] = st[i + 8] * da + Bt * x1;
;                     const f32x4 q0 = Ct * st[i], q1 = Ct * st[i + 8];
;                     const float p0 = (q0.x + q0.y) + (q0.z + q0.w), p1 = (q1.x + q1.y) + (q1.z + q1.w);
;                     const float send = up8 ? p0 : p1, keep = up8 ? p1 : p0; part[i] = keep + __shfl_xor(send, 8); } }
	v_pk_mul_f32 v[70:71], v[70:71], v[130:131] op_sel:[0,0] op_sel_hi:[1,0]
	v_pk_fma_f32 v[68:69], v[204:205], v[224:225], v[68:69] op_sel:[0,0,0] op_sel_hi:[1,0,1]
	v_pk_fma_f32 v[70:71], v[206:207], v[224:225], v[70:71] op_sel:[0,0,0] op_sel_hi:[1,0,1]
	v_pk_mul_f32 v[240:241], v[216:217], v[64:65]
	v_pk_fma_f32 v[240:241], v[218:219], v[66:67], v[240:241]
	v_pk_fma_f32 v[240:241], v[220:221], v[68:69], v[240:241]
	v_pk_fma_f32 v[240:241], v[222:223], v[70:71], v[240:241]
	v_add_f32_e32 v232, v240, v241
	v_pk_mul_f32 v[72:73], v[72:73], v[130:131] op_sel:[0,0] op_sel_hi:[1,0]
	v_pk_mul_f32 v[74:75], v[74:75], v[130:131] op_sel:[0,0] op_sel_hi:[1,0]
	v_pk_fma_f32 v[72:73], v[200:201], v[224:225], v[72:73] op_sel:[0,1,0] op_sel_hi:[1,1,1]
	v_pk_fma_f32 v[74:75], v[202:203], v[224:225], v[74:75] op_sel:[0,1,0] op_sel_hi:[1,1,1]
	v_pk_mul_f32 v[76:77], v[76:77], v[130:131] op_sel:[0,0] op_sel_hi:[1,0]
	v_pk_mul_f32 v[78:79], v[78:79], v[130:131] op_sel:[0,0] op_sel_hi:[1,0]
	v_pk_fma_f32 v[76:77], v[204:205], v[224:225], v[76:77] op_sel:[0,1,0] op_sel_hi:[1,1,1]
	v_pk_fma_f32 v[78:79], v[206:207], v[224:225], v[78:79] op_sel:[0,1,0] op_sel_hi:[1,1,1]
	v_pk_mul_f32 v[242:243], v[216:217], v[72:73]
	v_pk_fma_f32 v[242:243], v[218:219], v[74:75], v[242:243]
	v_pk_fma_f32 v[242:243], v[220:221], v[76:77], v[242:243]
	v_pk_fma_f32 v[242:243], v[222:223], v[78:79], v[242:243]
	v_add_f32_e32 v233, v242, v243
	v_pk_mul_f32 v[80:81], v[80:81], v[130:131] op_sel:[0,0] op_sel_hi:[1,0]
	v_pk_mul_f32 v[82:83], v[82:83], v[130:131] op_sel:[0,0] op_sel_hi:[1,0]
	v_pk_fma_f32 v[80:81], v[200:201], v[226:227], v[80:81] op_sel:[0,0,0] op_sel_hi:[1,0,1]
	v_pk_fma_f32 v[82:83], v[202:203], v[226:227], v[82:83] op_sel:[0,0,0] op_sel_hi:[1,0,1]
	v_pk_mul_f32 v[84:85], v[84:85], v[130:131] op_sel:[0,0] op_sel_hi:[1,0]
	v_pk_mul_f32 v[86:87], v[86:87], v[130:131] op_sel:[0,0] op_sel_hi:[1,0]
	v_pk_fma_f32 v[84:85], v[204:205], v[226:227], v[84:85] op_sel:[0,0,0] op_sel_hi:[1,0,1]
	v_pk_fma_f32 v[86:87], v[206:207], v[226:227], v[86:87] op_sel:[0,0,0] op_sel_hi:[1,0,1]
	v_pk_mul_f32 v[244:245], v[216:217], v[80:81]
	v_pk_fma_f32 v[244:245], v[218:219], v[82:83], v[244:245]
	v_pk_fma_f32 v[244:245], v[220:221], v[84:85], v[244:245]
	v_pk_fma_f32 v[244:245], v[222:223], v[86:87], v[244:245]
	v_add_f32_e32 v234, v244, v245
	v_pk_mul_f32 v[88:89], v[88:89], v[130:131] op_sel:[0,0] op_sel_hi:[1,0]
	v_pk_mul_f32 v[90:91], v[90:91], v[130:131] op_sel:[0,0] op_sel_hi:[1,0]
	v_pk_fma_f32 v[88:89], v[200:201], v[226:227], v[88:89] op_sel:[0,1,0] op_sel_hi:[1,1,1]
	v_pk_fma_f32 v[90:91], v[202:203], v[226:227], v[90:91] op_sel:[0,1,0] op_sel_hi:[1,1,1]
	v_pk_mul_f32 v[92:93], v[92:93], v[130:131] op_sel:[0,0] op_sel_hi:[1,0]
	v_pk_mul_f32 v[94:95], v[94:95], v[130:131] op_sel:[0,0] op_sel_hi:[1,0]
	v_pk_fma_f32 v[92:93], v[204:205], v[226:227], v[92:93] op_sel:[0,1,0] op_sel_hi:[1,1,1]
	v_pk_fma_f32 v[94:95], v[206:207], v[226:227], v[94:95] op_sel:[0,1,0] op_sel_hi:[1,1,1]
	v_pk_mul_f32 v[246:247], v[216:217], v[88:89]
	v_pk_fma_f32 v[246:247], v[218:219], v[90:91], v[246:247]
	v_pk_fma_f32 v[246:247], v[220:221], v[92:93], v[246:247]
	v_pk_fma_f32 v[246:247], v[222:223], v[94:95], v[246:247]
	v_add_f32_e32 v235, v246, v247
	v_pk_mul_f32 v[96:97], v[96:97], v[130:131] op_sel:[0,0] op_sel_hi:[1,0]
	v_pk_mul_f32 v[98:99], v[98:99], v[130:131] op_sel:[0,0] op_sel_hi:[1,0]
	v_pk_fma_f32 v[96:97], v[200:201], v[228:229], v[96:97] op_sel:[0,0,0] op_sel_hi:[1,0,1]
	v_pk_fma_f32 v[98:99], v[202:203], v[228:229], v[98:99] op_sel:[0,0,0] op_sel_hi:[1,0,1]
	v_pk_mul_f32 v[100:101], v[100:101], v[130:131] op_sel:[0,0] op_sel_hi:[1,0]
	v_pk_mul_f32 v[102:103], v[102:103], v[130:131] op_sel:[0,0] op_sel_hi:[1,0]
	v_pk_fma_f32 v[100:101], v[204:205], v[228:229], v[100:101] op_sel:[0,0,0] op_sel_hi:[1,0,1]
	v_pk_fma_f32 v[102:103], v[206:207], v[228:229], v[102:103] op_sel:[0,0,0] op_sel_hi:[1,0,1]
	v_pk_mul_f32 v[240:241], v[216:217], v[96:97]
	v_pk_fma_f32 v[240:241], v[218:219], v[98:99], v[240:241]
	v_pk_fma_f32 v[240:241], v[220:221], v[100:101], v[240:241]
	v_pk_fma_f32 v[240:241], v[222:223], v[102:103], v[240:241]
	v_add_f32_e32 v236, v240, v241
	v_pk_mul_f32 v[104:105], v[104:105], v[130:131] op_sel:[0,0] op_sel_hi:[1,0]
	v_pk_mul_f32 v[106:107], v[106:107], v[130:131] op_sel:[0,0] op_sel_hi:[1,0]
	v_pk_fma_f32 v[104:105], v[200:201], v[228:229], v[104:105] op_sel:[0,1,0] op_sel_hi:[1,1,1]
	v_pk_fma_f32 v[106:107], v[202:203], v[228:229], v[106:107] op_sel:[0,1,0] op_sel_hi:[1,1,1]
	v_pk_mul_f32 v[108:109], v[108:109], v[130:131] op_sel:[0,0] op_sel_hi:[1,0]
	v_pk_mul_f32 v[110:111], v[110:111], v[130:131] op_sel:[0,0] op_sel_hi:[1,0]
	v_pk_fma_f32 v[108:109], v[204:205], v[228:229], v[108:109] op_sel:[0,1,0] op_sel_hi:[1,1,1]
	v_pk_fma_f32 v[110:111], v[206:207], v[228:229], v[110:111] op_sel:[0,1,0] op_sel_hi:[1,1,1]
	v_pk_mul_f32 v[242:243], v[216:217], v[104:105]
	v_pk_fma_f32 v[242:243], v[218:219], v[106:107], v[242:243]
	v_pk_fma_f32 v[242:243], v[220:221], v[108:109], v[242:243]
	v_pk_fma_f32 v[242:243], v[222:223], v[110:111], v[242:243]
	v_add_f32_e32 v237, v242, v243
	v_pk_mul_f32 v[112:113], v[112:113], v[130:131] op_sel:[0,0] op_sel_hi:[1,0]
	v_pk_mul_f32 v[114:115], v[114:115], v[130:131] op_sel:[0,0] op_sel_hi:[1,0]
	v_pk_fma_f32 v[112:113], v[200:201], v[230:231], v[112:113] op_sel:[0,0,0] op_sel_hi:[1,0,1]
	v_pk_fma_f32 v[114:115], v[202:203], v[230:231], v[114:115] op_sel:[0,0,0] op_sel_hi:[1,0,1]
	v_pk_mul_f32 v[116:117], v[116:117], v[130:131] op_sel:[0,0] op_sel_hi:[1,0]
	v_pk_mul_f32 v[118:119], v[118:119], v[130:131] op_sel:[0,0] op_sel_hi:[1,0]
; __device__ __forceinline__ unsigned f2bf(float f) { unsigned u = __float_as_uint(f); return (u + 0x7fffu + ((u >> 16) & 1u)) >> 16; }
; #define BFLY(o) do { const bool up = (nl & (o)) != 0; _Pragma("unroll") for (int i = 0; i < (o); ++i) { \
;                     const float send = up ? part[i] : part[i + (o)]; const float keep = up ? part[i + (o)] : part[i]; part[i] = keep + __shfl_xor(send, (o)); } } while (0)
; __device__ __forceinline__ void ssd_sample_items(LAS unsigned char* lds, int it0, int itstride, int nitems, const bf16_t* XBC, const float* DT, const float* a_log,
;                                                  const float* state_in, bf16_t* MIX, float* s_ssm) {
;     ...
;                   for (int i = 0; i < 8; ++i) {
;                     const float x0 = Xs[t * 512 + w * 64 + 32 * hh + 2 * i + half], x1 = Xs[t * 512 + w * 64 + 32 * hh + 2 * (i + 8) + half];
;                     st[i] = st[i] * da + Bt * x0; st[i + 8] = st[i + 8] * da + Bt * x1;
;                     const f32x4 q0 = Ct * st[i], q1 = Ct * st[i + 8];
;                     const float p0 = (q0.x + q0.y) + (q0.z + q0.w), p1 = (q1.x + q1.y) + (q1.z + q1.w);
;                     const float send = up8 ? p0 : p1, keep = up8 ? p1 : p0; part[i] = keep + __shfl_xor(send, 8); } }
;     ...
;                 BFLY(4); BFLY(2); BFLY(1);
;     ...
;                 yv[t] = part[0] + __shfl_xor(part[0], 16);
;             }
;             const int pout = 32 * hh + 2 * (nl & 15) + half;
;             if ((nl & 16) == 0) {
; #pragma unroll
;                 for (int t = 0; t < 4; ++t) MIX[(size_t)(MP + 4 * b + t) * DMIX + h * 64 + pout] = (bf16_t)f2bf(yv[t]);
;             }
	v_pk_fma_f32 v[116:117], v[204:205], v[230:231], v[116:117] op_sel:[0,0,0] op_sel_hi:[1,0,1]
	v_pk_fma_f32 v[118:119], v[206:207], v[230:231], v[118:119] op_sel:[0,0,0] op_sel_hi:[1,0,1]
	v_pk_mul_f32 v[244:245], v[216:217], v[112:113]
	v_pk_fma_f32 v[244:245], v[218:219], v[114:115], v[244:245]
	v_pk_fma_f32 v[244:245], v[220:221], v[116:117], v[244:245]
	v_pk_fma_f32 v[244:245], v[222:223], v[118:119], v[244:245]
	v_add_f32_e32 v238, v244, v245
	v_pk_mul_f32 v[120:121], v[120:121], v[130:131] op_sel:[0,0] op_sel_hi:[1,0]
	v_pk_mul_f32 v[122:123], v[122:123], v[130:131] op_sel:[0,0] op_sel_hi:[1,0]
	v_pk_fma_f32 v[120:121], v[200:201], v[230:231], v[120:121] op_sel:[0,1,0] op_sel_hi:[1,1,1]
	v_pk_fma_f32 v[122:123], v[202:203], v[230:231], v[122:123] op_sel:[0,1,0] op_sel_hi:[1,1,1]
	v_pk_mul_f32 v[124:125], v[124:125], v[130:131] op_sel:[0,0] op_sel_hi:[1,0]
	v_pk_mul_f32 v[126:127], v[126:127], v[130:131] op_sel:[0,0] op_sel_hi:[1,0]
	v_pk_fma_f32 v[124:125], v[204:205], v[230:231], v[124:125] op_sel:[0,1,0] op_sel_hi:[1,1,1]
	v_pk_fma_f32 v[126:127], v[206:207], v[230:231], v[126:127] op_sel:[0,1,0] op_sel_hi:[1,1,1]
	v_pk_mul_f32 v[246:247], v[216:217], v[120:121]
	v_pk_fma_f32 v[246:247], v[218:219], v[122:123], v[246:247]
	v_pk_fma_f32 v[246:247], v[220:221], v[124:125], v[246:247]
	v_pk_fma_f32 v[246:247], v[222:223], v[126:127], v[246:247]
	v_add_f32_e32 v239, v246, v247
	v_add_f32_dpp v232, v232, v232 row_mirror row_mask:0xf bank_mask:0x3
	v_add_f32_dpp v232, v236, v236 row_mirror row_mask:0xf bank_mask:0xc
	v_add_f32_dpp v233, v233, v233 row_mirror row_mask:0xf bank_mask:0x3
	v_add_f32_dpp v233, v237, v237 row_mirror row_mask:0xf bank_mask:0xc
	v_add_f32_dpp v234, v234, v234 row_mirror row_mask:0xf bank_mask:0x3
	v_add_f32_dpp v234, v238, v238 row_mirror row_mask:0xf bank_mask:0xc
	v_add_f32_dpp v235, v235, v235 row_mirror row_mask:0xf bank_mask:0x3
	v_add_f32_dpp v235, v239, v239 row_mirror row_mask:0xf bank_mask:0xc
	v_add_f32_dpp v232, v232, v232 row_half_mirror row_mask:0xf bank_mask:0x5
	v_add_f32_dpp v232, v234, v234 row_half_mirror row_mask:0xf bank_mask:0xa
	v_add_f32_dpp v233, v233, v233 row_half_mirror row_mask:0xf bank_mask:0x5
	v_add_f32_dpp v233, v235, v235 row_half_mirror row_mask:0xf bank_mask:0xa
	v_add_f32_dpp v248, v232, v232 quad_perm:[2,3,0,1] row_mask:0xf bank_mask:0xf
	s_nop 0
	v_add_f32_dpp v249, v233, v233 quad_perm:[2,3,0,1] row_mask:0xf bank_mask:0xf
	v_cndmask_b32_e64 v232, v248, v249, s[68:69]
	s_nop 1
	v_add_f32_dpp v233, v232, v232 quad_perm:[1,0,3,2] row_mask:0xf bank_mask:0xf
	v_cvt_pk_bf16_f32 v214, v233, v233
	s_mov_b64 exec, s[38:39]
	global_store_short v213, v214, s[8:9] offset:64
	s_mov_b64 exec, -1
	v_lshlrev_b32_e32 v224, 16, v196
	v_and_b32_e32 v225, 0xffff0000, v196
	v_lshlrev_b32_e32 v226, 16, v197
	v_and_b32_e32 v227, 0xffff0000, v197
	v_lshlrev_b32_e32 v228, 16, v198
	v_and_b32_e32 v229, 0xffff0000, v198
	v_lshlrev_b32_e32 v230, 16, v199
	v_and_b32_e32 v231, 0xffff0000, v199
	v_lshlrev_b32_e32 v200, 16, v148
	v_and_b32_e32 v201, 0xffff0000, v148
	v_lshlrev_b32_e32 v202, 16, v149
	v_and_b32_e32 v203, 0xffff0000, v149
	v_lshlrev_b32_e32 v204, 16, v150
	v_and_b32_e32 v205, 0xffff0000, v150
	v_lshlrev_b32_e32 v206, 16, v151
	v_and_b32_e32 v207, 0xffff0000, v151
	v_lshlrev_b32_e32 v216, 16, v164
	v_and_b32_e32 v217, 0xffff0000, v164
	v_lshlrev_b32_e32 v218, 16, v165
	v_and_b32_e32 v219, 0xffff0000, v165
	v_lshlrev_b32_e32 v220, 16, v166
	v_and_b32_e32 v221, 0xffff0000, v166
	v_lshlrev_b32_e32 v222, 16, v167
	v_and_b32_e32 v223, 0xffff0000, v167
	v_pk_mul_f32 v[200:201], v[200:201], v[210:211] op_sel:[0,1] op_sel_hi:[1,1]
	v_pk_mul_f32 v[202:203], v[202:203], v[210:211] op_sel:[0,1] op_sel_hi:[1,1]
	v_pk_mul_f32 v[204:205], v[204:205], v[210:211] op_sel:[0,1] op_sel_hi:[1,1]
	v_pk_mul_f32 v[206:207], v[206:207], v[210:211] op_sel:[0,1] op_sel_hi:[1,1]
	v_pk_mul_f32 v[64:65], v[64:65], v[130:131] op_sel:[0,1] op_sel_hi:[1,1]
	v_pk_mul_f32 v[66:67], v[66:67], v[130:131] op_sel:[0,1] op_sel_hi:[1,1]
	v_pk_fma_f32 v[64:65], v[200:201], v[224:225], v[64:65] op_sel:[0,0,0] op_sel_hi:[1,0,1]
	v_pk_fma_f32 v[66:67], v[202:203], v[224:225], v[66:67] op_sel:[0,0,0] op_sel_hi:[1,0,1]
	v_pk_mul_f32 v[68:69], v[68:69], v[130:131] op_sel:[0,1] op_sel_hi:[1,1]
	v_pk_mul_f32 v[70:71], v[70:71], v[130:131] op_sel:[0,1] op_sel_hi:[1,1]
	v_pk_fma_f32 v[68:69], v[204:205], v[224:225], v[68:69] op_sel:[0,0,0] op_sel_hi:[1,0,1]
	v_pk_fma_f32 v[70:71], v[206:207], v[224:225], v[70:71] op_sel:[0,0,0] op_sel_hi:[1,0,1]
	v_pk_mul_f32 v[240:241], v[216:217], v[64:65]
	v_pk_fma_f32 v[240:241], v[218:219], v[66:67], v[240:241]
	v_pk_fma_f32 v[240:241], v[220:221], v[68:69], v[240:241]
	v_pk_fma_f32 v[240:241], v[222:223], v[70:71], v[240:241]
	v_add_f32_e32 v232, v240, v241
	v_pk_mul_f32 v[72:73], v[72:73], v[130:131] op_sel:[0,1] op_sel_hi:[1,1]
	v_pk_mul_f32 v[74:75], v[74:75], v[130:131] op_sel:[0,1] op_sel_hi:[1,1]
	v_pk_fma_f32 v[72:73], v[200:201], v[224:225], v[72:73] op_sel:[0,1,0] op_sel_hi:[1,1,1]
	v_pk_fma_f32 v[74:75], v[202:203], v[224:225], v[74:75] op_sel:[0,1,0] op_sel_hi:[1,1,1]
	v_pk_mul_f32 v[76:77], v[76:77], v[130:131] op_sel:[0,1] op_sel_hi:[1,1]
	v_pk_mul_f32 v[78:79], v[78:79], v[130:131] op_sel:[0,1] op_sel_hi:[1,1]
	v_pk_fma_f32 v[76:77], v[204:205], v[224:225], v[76:77] op_sel:[0,1,0] op_sel_hi:[1,1,1]
	v_pk_fma_f32 v[78:79], v[206:207], v[224:225], v[78:79] op_sel:[0,1,0] op_sel_hi:[1,1,1]
	v_pk_mul_f32 v[242:243], v[216:217], v[72:73]
	v_pk_fma_f32 v[242:243], v[218:219], v[74:75], v[242:243]
	v_pk_fma_f32 v[242:243], v[220:221], v[76:77], v[242:243]
	v_pk_fma_f32 v[242:243], v[222:223], v[78:79], v[242:243]
; __device__ __forceinline__ void ssd_sample_items(LAS unsigned char* lds, int it0, int itstride, int nitems, const bf16_t* XBC, const float* DT, const float* a_log,
;                                                  const float* state_in, bf16_t* MIX, float* s_ssm) {
;     ...
;                   for (int i = 0; i < 8; ++i) {
;                     const float x0 = Xs[t * 512 + w * 64 + 32 * hh + 2 * i + half], x1 = Xs[t * 512 + w * 64 + 32 * hh + 2 * (i + 8) + half];
;                     st[i] = st[i] * da + Bt * x0; st[i + 8] = st[i + 8] * da + Bt * x1;
;                     const f32x4 q0 = Ct * st[i], q1 = Ct * st[i + 8];
;                     const float p0 = (q0.x + q0.y) + (q0.z + q0.w), p1 = (q1.x + q1.y) + (q1.z + q1.w);
;                     const float send = up8 ? p0 : p1, keep = up8 ? p1 : p0; part[i] = keep + __shfl_xor(send, 8); } }
	v_add_f32_e32 v233, v242, v243
	v_pk_mul_f32 v[80:81], v[80:81], v[130:131] op_sel:[0,1] op_sel_hi:[1,1]
	v_pk_mul_f32 v[82:83], v[82:83], v[130:131] op_sel:[0,1] op_sel_hi:[1,1]
	v_pk_fma_f32 v[80:81], v[200:201], v[226:227], v[80:81] op_sel:[0,0,0] op_sel_hi:[1,0,1]
	v_pk_fma_f32 v[82:83], v[202:203], v[226:227], v[82:83] op_sel:[0,0,0] op_sel_hi:[1,0,1]
	v_pk_mul_f32 v[84:85], v[84:85], v[130:131] op_sel:[0,1] op_sel_hi:[1,1]
	v_pk_mul_f32 v[86:87], v[86:87], v[130:131] op_sel:[0,1] op_sel_hi:[1,1]
	v_pk_fma_f32 v[84:85], v[204:205], v[226:227], v[84:85] op_sel:[0,0,0] op_sel_hi:[1,0,1]
	v_pk_fma_f32 v[86:87], v[206:207], v[226:227], v[86:87] op_sel:[0,0,0] op_sel_hi:[1,0,1]
	v_pk_mul_f32 v[244:245], v[216:217], v[80:81]
	v_pk_fma_f32 v[244:245], v[218:219], v[82:83], v[244:245]
	v_pk_fma_f32 v[244:245], v[220:221], v[84:85], v[244:245]
	v_pk_fma_f32 v[244:245], v[222:223], v[86:87], v[244:245]
	v_add_f32_e32 v234, v244, v245
	v_pk_mul_f32 v[88:89], v[88:89], v[130:131] op_sel:[0,1] op_sel_hi:[1,1]
	v_pk_mul_f32 v[90:91], v[90:91], v[130:131] op_sel:[0,1] op_sel_hi:[1,1]
	v_pk_fma_f32 v[88:89], v[200:201], v[226:227], v[88:89] op_sel:[0,1,0] op_sel_hi:[1,1,1]
	v_pk_fma_f32 v[90:91], v[202:203], v[226:227], v[90:91] op_sel:[0,1,0] op_sel_hi:[1,1,1]
	v_pk_mul_f32 v[92:93], v[92:93], v[130:131] op_sel:[0,1] op_sel_hi:[1,1]
	v_pk_mul_f32 v[94:95], v[94:95], v[130:131] op_sel:[0,1] op_sel_hi:[1,1]
	v_pk_fma_f32 v[92:93], v[204:205], v[226:227], v[92:93] op_sel:[0,1,0] op_sel_hi:[1,1,1]
	v_pk_fma_f32 v[94:95], v[206:207], v[226:227], v[94:95] op_sel:[0,1,0] op_sel_hi:[1,1,1]
	v_pk_mul_f32 v[246:247], v[216:217], v[88:89]
	v_pk_fma_f32 v[246:247], v[218:219], v[90:91], v[246:247]
	v_pk_fma_f32 v[246:247], v[220:221], v[92:93], v[246:247]
	v_pk_fma_f32 v[246:247], v[222:223], v[94:95], v[246:247]
	v_add_f32_e32 v235, v246, v247
	v_pk_mul_f32 v[96:97], v[96:97], v[130:131] op_sel:[0,1] op_sel_hi:[1,1]
	v_pk_mul_f32 v[98:99], v[98:99], v[130:131] op_sel:[0,1] op_sel_hi:[1,1]
	v_pk_fma_f32 v[96:97], v[200:201], v[228:229], v[96:97] op_sel:[0,0,0] op_sel_hi:[1,0,1]
	v_pk_fma_f32 v[98:99], v[202:203], v[228:229], v[98:99] op_sel:[0,0,0] op_sel_hi:[1,0,1]
	v_pk_mul_f32 v[100:101], v[100:101], v[130:131] op_sel:[0,1] op_sel_hi:[1,1]
	v_pk_mul_f32 v[102:103], v[102:103], v[130:131] op_sel:[0,1] op_sel_hi:[1,1]
	v_pk_fma_f32 v[100:101], v[204:205], v[228:229], v[100:101] op_sel:[0,0,0] op_sel_hi:[1,0,1]
	v_pk_fma_f32 v[102:103], v[206:207], v[228:229], v[102:103] op_sel:[0,0,0] op_sel_hi:[1,0,1]
	v_pk_mul_f32 v[240:241], v[216:217], v[96:97]
	v_pk_fma_f32 v[240:241], v[218:219], v[98:99], v[240:241]
	v_pk_fma_f32 v[240:241], v[220:221], v[100:101], v[240:241]
	v_pk_fma_f32 v[240:241], v[222:223], v[102:103], v[240:241]
	v_add_f32_e32 v236, v240, v241
	v_pk_mul_f32 v[104:105], v[104:105], v[130:131] op_sel:[0,1] op_sel_hi:[1,1]
	v_pk_mul_f32 v[106:107], v[106:107], v[130:131] op_sel:[0,1] op_sel_hi:[1,1]
	v_pk_fma_f32 v[104:105], v[200:201], v[228:229], v[104:105] op_sel:[0,1,0] op_sel_hi:[1,1,1]
	v_pk_fma_f32 v[106:107], v[202:203], v[228:229], v[106:107] op_sel:[0,1,0] op_sel_hi:[1,1,1]
	v_pk_mul_f32 v[108:109], v[108:109], v[130:131] op_sel:[0,1] op_sel_hi:[1,1]
	v_pk_mul_f32 v[110:111], v[110:111], v[130:131] op_sel:[0,1] op_sel_hi:[1,1]
	v_pk_fma_f32 v[108:109], v[204:205], v[228:229], v[108:109] op_sel:[0,1,0] op_sel_hi:[1,1,1]
	v_pk_fma_f32 v[110:111], v[206:207], v[228:229], v[110:111] op_sel:[0,1,0] op_sel_hi:[1,1,1]
	v_pk_mul_f32 v[242:243], v[216:217], v[104:105]
	v_pk_fma_f32 v[242:243], v[218:219], v[106:107], v[242:243]
	v_pk_fma_f32 v[242:243], v[220:221], v[108:109], v[242:243]
	v_pk_fma_f32 v[242:243], v[222:223], v[110:111], v[242:243]
	v_add_f32_e32 v237, v242, v243
	v_pk_mul_f32 v[112:113], v[112:113], v[130:131] op_sel:[0,1] op_sel_hi:[1,1]
	v_pk_mul_f32 v[114:115], v[114:115], v[130:131] op_sel:[0,1] op_sel_hi:[1,1]
	v_pk_fma_f32 v[112:113], v[200:201], v[230:231], v[112:113] op_sel:[0,0,0] op_sel_hi:[1,0,1]
	v_pk_fma_f32 v[114:115], v[202:203], v[230:231], v[114:115] op_sel:[0,0,0] op_sel_hi:[1,0,1]
	v_pk_mul_f32 v[116:117], v[116:117], v[130:131] op_sel:[0,1] op_sel_hi:[1,1]
	v_pk_mul_f32 v[118:119], v[118:119], v[130:131] op_sel:[0,1] op_sel_hi:[1,1]
	v_pk_fma_f32 v[116:117], v[204:205], v[230:231], v[116:117] op_sel:[0,0,0] op_sel_hi:[1,0,1]
	v_pk_fma_f32 v[118:119], v[206:207], v[230:231], v[118:119] op_sel:[0,0,0] op_sel_hi:[1,0,1]
	v_pk_mul_f32 v[244:245], v[216:217], v[112:113]
	v_pk_fma_f32 v[244:245], v[218:219], v[114:115], v[244:245]
	v_pk_fma_f32 v[244:245], v[220:221], v[116:117], v[244:245]
	v_pk_fma_f32 v[244:245], v[222:223], v[118:119], v[244:245]
	v_add_f32_e32 v238, v244, v245
	v_pk_mul_f32 v[120:121], v[120:121], v[130:131] op_sel:[0,1] op_sel_hi:[1,1]
	v_pk_mul_f32 v[122:123], v[122:123], v[130:131] op_sel:[0,1] op_sel_hi:[1,1]
	v_pk_fma_f32 v[120:121], v[200:201], v[230:231], v[120:121] op_sel:[0,1,0] op_sel_hi:[1,1,1]
	v_pk_fma_f32 v[122:123], v[202:203], v[230:231], v[122:123] op_sel:[0,1,0] op_sel_hi:[1,1,1]
	v_pk_mul_f32 v[124:125], v[124:125], v[130:131] op_sel:[0,1] op_sel_hi:[1,1]
	v_pk_mul_f32 v[126:127], v[126:127], v[130:131] op_sel:[0,1] op_sel_hi:[1,1]
	v_pk_fma_f32 v[124:125], v[204:205], v[230:231], v[124:125] op_sel:[0,1,0] op_sel_hi:[1,1,1]
	v_pk_fma_f32 v[126:127], v[206:207], v[230:231], v[126:127] op_sel:[0,1,0] op_sel_hi:[1,1,1]
	v_pk_mul_f32 v[246:247], v[216:217], v[120:121]
	v_pk_fma_f32 v[246:247], v[218:219], v[122:123], v[246:247]
	v_pk_fma_f32 v[246:247], v[220:221], v[124:125], v[246:247]
	v_pk_fma_f32 v[246:247], v[222:223], v[126:127], v[246:247]
	v_add_f32_e32 v239, v246, v247
; __device__ __forceinline__ void ssd_sample_items(LAS unsigned char* lds, int it0, int itstride, int nitems, const bf16_t* XBC, const float* DT, const float* a_log,
;                                                  const float* state_in, bf16_t* MIX, float* s_ssm) {
;     ...
;     for (int it = it0; it < nitems; it += itstride) {
;         const int b = it >> 2, g = it & 3, h = g * 8 + w;
;         u32x2 Bp[4], Cp[4]; float dtv[4];
; #pragma unroll
;         for (int t = 0; t < 4; ++t) { const size_t row = (size_t)(MP + 4 * b + t);
;             Xs[t * 512 + tid] = bf2f(XBC[row * XBCW + g * 512 + tid]);
;             Bp[t] = *(const u32x2*)(XBC + row * XBCW + 2048 + g * 128 + 4 * nl); Cp[t] = *(const u32x2*)(XBC + row * XBCW + 2560 + g * 128 + 4 * nl);
;             dtv[t] = DT[row * NH + h]; }
;         const float A = -__expf(a_log[h]);
;         LDS_BARRIER();
; #pragma unroll
;         for (int hh = 0; hh < 2; ++hh) {
;             f32x4 st[16];
; #pragma unroll
;             for (int k = 0; k < 16; ++k) st[k] = nx[k];
;             {
;                 const int itn = it + itstride;
;                 if (hh == 0) { const float* sp = state_in + (size_t)(b * NH + h) * HP * NS + 4096;
; #pragma unroll
;                     for (int k = 0; k < 16; ++k) nx[k] = *(const f32x4*)(sp + k * 256 + lane * 4); }
;                 else if (itn < nitems) { const int bn = itn >> 2, gn = itn & 3; const float* sp = state_in + (size_t)(bn * NH + gn * 8 + w) * HP * NS;
; #pragma unroll
;                     for (int k = 0; k < 16; ++k) nx[k] = *(const f32x4*)(sp + k * 256 + lane * 4); }
;             }
;             float yv[4];
; #pragma unroll
;             for (int t = 0; t < 4; ++t) {
;                 const float dt = dtv[t]; const float da = __expf(dt * A);
;                 const f32x4 Bt = (f32x4){bf2f(Bp[t].x & 0xffffu), bf2f(Bp[t].x >> 16), bf2f(Bp[t].y & 0xffffu), bf2f(Bp[t].y >> 16)} * dt;
;                 const f32x4 Ct = (f32x4){bf2f(Cp[t].x & 0xffffu), bf2f(Cp[t].x >> 16), bf2f(Cp[t].y & 0xffffu), bf2f(Cp[t].y >> 16)};
;                 float part[8];
;                 { const bool up8 = (nl & 8) != 0;
; #pragma unroll
;                   for (int i = 0; i < 8; ++i) {
;                     const float x0 = Xs[t * 512 + w * 64 + 32 * hh + 2 * i + half], x1 = Xs[t * 512 + w * 64 + 32 * hh + 2 * (i + 8) + half];
	v_add_f32_dpp v232, v232, v232 row_mirror row_mask:0xf bank_mask:0x3
	v_add_f32_dpp v232, v236, v236 row_mirror row_mask:0xf bank_mask:0xc
	v_add_f32_dpp v233, v233, v233 row_mirror row_mask:0xf bank_mask:0x3
	v_add_f32_dpp v233, v237, v237 row_mirror row_mask:0xf bank_mask:0xc
	v_add_f32_dpp v234, v234, v234 row_mirror row_mask:0xf bank_mask:0x3
	v_add_f32_dpp v234, v238, v238 row_mirror row_mask:0xf bank_mask:0xc
	v_add_f32_dpp v235, v235, v235 row_mirror row_mask:0xf bank_mask:0x3
	v_add_f32_dpp v235, v239, v239 row_mirror row_mask:0xf bank_mask:0xc
	v_add_f32_dpp v232, v232, v232 row_half_mirror row_mask:0xf bank_mask:0x5
	v_add_f32_dpp v232, v234, v234 row_half_mirror row_mask:0xf bank_mask:0xa
	v_add_f32_dpp v233, v233, v233 row_half_mirror row_mask:0xf bank_mask:0x5
	v_add_f32_dpp v233, v235, v235 row_half_mirror row_mask:0xf bank_mask:0xa
	v_add_f32_dpp v248, v232, v232 quad_perm:[2,3,0,1] row_mask:0xf bank_mask:0xf
	s_nop 0
	v_add_f32_dpp v249, v233, v233 quad_perm:[2,3,0,1] row_mask:0xf bank_mask:0xf
	v_cndmask_b32_e64 v232, v248, v249, s[68:69]
	s_nop 1
	v_add_f32_dpp v233, v232, v232 quad_perm:[1,0,3,2] row_mask:0xf bank_mask:0xf
	v_cvt_pk_bf16_f32 v214, v233, v233
	s_mov_b64 exec, s[38:39]
	global_store_short v213, v214, s[10:11] offset:64
	s_mov_b64 exec, -1
	s_mov_b32 s12, s56
	s_mov_b32 s13, s57
	s_add_u32 s47, s47, s33
	s_cmpk_lt_u32 s47, 512
	s_cbranch_scc0 .Lssds_last
	s_lshr_b32 s20, s47, 2
	s_and_b32 s21, s47, 3
	s_lshl_b32 s22, s21, 3
	s_add_u32 s22, s22, s46
	s_lshl_b32 s23, s20, 5
	s_add_u32 s23, s23, s22
	s_lshr_b32 s51, s23, 17
	s_lshl_b32 s50, s23, 15
	s_add_u32 s52, s18, s50
	s_addc_u32 s53, s19, s51
	s_add_u32 s50, s14, s50
	s_addc_u32 s51, s15, s51
	s_add_u32 s54, s50, 0x4000
	s_addc_u32 s55, s51, 0
	s_add_u32 s56, s52, 0x4000
	s_addc_u32 s57, s53, 0
	s_lshl_b32 s20, s20, 2
	s_add_u32 s20, s20, 0x2000
	s_lshl_b32 s23, s22, 7
	s_mul_hi_u32 s59, s20, 0x1800
	s_mul_i32 s58, s20, 0x1800
	s_add_u32 s58, s58, s40
	s_addc_u32 s59, s59, s41
	s_add_u32 s58, s58, s23
	s_addc_u32 s59, s59, 0
	s_add_u32 s60, s58, 0x1800
	s_addc_u32 s61, s59, 0
	s_add_u32 s62, s60, 0x1800
	s_addc_u32 s63, s61, 0
	s_add_u32 s64, s62, 0x1800
	s_addc_u32 s65, s63, 0
	s_lshr_b32 s5, s20, 19
	s_lshl_b32 s4, s20, 13
	s_add_u32 s4, s4, s44
	s_addc_u32 s5, s5, s45
	s_add_u32 s4, s4, s23
	s_addc_u32 s5, s5, 0
	s_add_u32 s6, s4, 0x2000
	s_addc_u32 s7, s5, 0
	s_add_u32 s8, s6, 0x2000
	s_addc_u32 s9, s7, 0
	s_add_u32 s10, s8, 0x2000
	s_addc_u32 s11, s9, 0
	s_lshl_b32 s23, s22, 2
	s_lshr_b32 s21, s20, 25
	s_lshl_b32 s20, s20, 7
	s_add_u32 s20, s20, s42
	s_addc_u32 s21, s21, s43
	s_add_u32 s20, s20, s23
	s_addc_u32 s21, s21, 0
	global_load_dword v208, v250, s[20:21] offset:0
	global_load_dword v209, v250, s[20:21] offset:128
	global_load_dword v210, v250, s[20:21] offset:256
	global_load_dword v211, v250, s[20:21] offset:384
	s_nop 0
	s_add_u32 s20, s16, s23
	s_addc_u32 s21, s17, 0
	s_load_dword s36, s[20:21], 0x0
	s_and_b32 s20, s47, 3
	s_lshl_b32 s20, s20, 8
	s_lshl_b32 s21, s22, 7
	s_sub_u32 s20, s20, s21
	s_add_u32 s20, s20, 0x1000
	s_add_u32 s22, s58, s20
	s_addc_u32 s23, s59, 0
	global_load_dwordx2 v[136:137], v134, s[22:23]
	global_load_dwordx2 v[138:139], v134, s[22:23] offset:128
	global_load_dwordx2 v[152:153], v134, s[22:23] offset:1024
	global_load_dwordx2 v[154:155], v134, s[22:23] offset:1152
	s_add_u32 s22, s60, s20
	s_addc_u32 s23, s61, 0
	global_load_dwordx2 v[140:141], v134, s[22:23]
	global_load_dwordx2 v[142:143], v134, s[22:23] offset:128
	global_load_dwordx2 v[156:157], v134, s[22:23] offset:1024
	global_load_dwordx2 v[158:159], v134, s[22:23] offset:1152
	s_add_u32 s22, s62, s20
	s_addc_u32 s23, s63, 0
	global_load_dwordx2 v[144:145], v134, s[22:23]
	global_load_dwordx2 v[146:147], v134, s[22:23] offset:128
	global_load_dwordx2 v[160:161], v134, s[22:23] offset:1024
	global_load_dwordx2 v[162:163], v134, s[22:23] offset:1152
	s_add_u32 s22, s64, s20
	s_addc_u32 s23, s65, 0
	global_load_dwordx2 v[148:149], v134, s[22:23]
	global_load_dwordx2 v[150:151], v134, s[22:23] offset:128
	global_load_dwordx2 v[164:165], v134, s[22:23] offset:1024
	global_load_dwordx2 v[166:167], v134, s[22:23] offset:1152
	global_load_dwordx4 v[168:171], v133, s[58:59] offset:0
	global_load_dwordx4 v[184:187], v133, s[58:59] offset:64
	global_load_dwordx4 v[172:175], v133, s[60:61] offset:0
	global_load_dwordx4 v[188:191], v133, s[60:61] offset:64
	global_load_dwordx4 v[176:179], v133, s[62:63] offset:0
	global_load_dwordx4 v[192:195], v133, s[62:63] offset:64
	global_load_dwordx4 v[180:183], v133, s[64:65] offset:0
	global_load_dwordx4 v[196:199], v133, s[64:65] offset:64
	global_store_dwordx4 v132, v[64:67], s[12:13] offset:0
	global_store_dwordx4 v132, v[68:71], s[12:13] offset:256
	global_store_dwordx4 v132, v[72:75], s[12:13] offset:512
	global_store_dwordx4 v132, v[76:79], s[12:13] offset:768
	global_store_dwordx4 v132, v[80:83], s[12:13] offset:1024
	global_store_dwordx4 v132, v[84:87], s[12:13] offset:1280
	global_store_dwordx4 v132, v[88:91], s[12:13] offset:1536
	global_store_dwordx4 v132, v[92:95], s[12:13] offset:1792
	global_store_dwordx4 v132, v[96:99], s[12:13] offset:2048
	global_store_dwordx4 v132, v[100:103], s[12:13] offset:2304
	global_store_dwordx4 v132, v[104:107], s[12:13] offset:2560
	global_store_dwordx4 v132, v[108:111], s[12:13] offset:2816
	global_store_dwordx4 v132, v[112:115], s[12:13] offset:3072
	global_store_dwordx4 v132, v[116:119], s[12:13] offset:3328
	global_store_dwordx4 v132, v[120:123], s[12:13] offset:3584
	global_store_dwordx4 v132, v[124:127], s[12:13] offset:3840
	s_branch .Lssds_unit
